# gemm_up: second resident block of each CU starts ~2.7us later so its conv-gate VALU epilogue overlaps the other block's matrix loop; scan fast paths for 64-chunk sequences
# speedup vs baseline: 1.0221x; 1.0022x over previous
.LBB0_1070:
	s_or_b64 exec, exec, s[0:1]
	v_lshl_add_u32 v17, v16, 11, v250
	v_lshlrev_b32_e32 v19, 8, v16
	v_cmp_gt_i32_e32 vcc, 16, v16
	v_lshlrev_b32_e32 v228, 8, v15
	v_lshl_add_u64 v[28:29], v[24:25], 2, v[6:7]
	v_cndmask_b32_e32 v19, v17, v19, vcc
	v_cndmask_b32_e64 v17, 64, 8, vcc
	v_lshl_add_u64 v[28:29], v[28:29], 0, v[228:229]
	v_mov_b32_e32 v15, v229
	v_ashrrev_i32_e32 v19, 5, v19
	s_mov_b32 s11, 0
	v_cmp_eq_u32_e64 s[2:3], 0, v21
	v_lshl_add_u64 v[26:27], v[10:11], 0, v[228:229]
	v_lshl_add_u64 v[28:29], v[28:29], 0, v[14:15]
	v_add_u32_e32 v15, -1, v17
	s_mov_b64 s[8:9], 0
	v_cmp_ne_u32_e64 s[0:1], 64, v17
	s_cmp_lg_u64 s[0:1], 0
	s_cbranch_scc1 .LBB0_1071
	s_waitcnt vmcnt(0) lgkmcnt(0)
	v_mov_b32_e32 v23, s11
	v_cndmask_b32_e64 v23, v15, v23, s[2:3]
	v_add_u32_e32 v23, v23, v19
	v_lshl_or_b32 v30, v23, 1, v21
	v_ashrrev_i32_e32 v31, 31, v30
	v_lshlrev_b64 v[32:33], 2, v[30:31]
	v_or_b32_e32 v32, v32, v20
	v_lshlrev_b64 v[34:35], 14, v[32:33]
	v_lshlrev_b64 v[32:33], 8, v[32:33]
	v_lshl_add_u64 v[32:33], v[12:13], 0, v[32:33]
	s_xor_b32 s0, s11, 0x7ffffffe
	global_load_dword v45, v[32:33], off
	v_add_u32_e32 v32, s0, v17
	s_add_i32 s0, s11, 1
	v_mov_b32_e32 v33, s0
	v_cndmask_b32_e64 v32, v32, v33, s[2:3]
	v_add_u32_e32 v32, v32, v19
	v_lshl_or_b32 v32, v32, 1, v21
	v_lshl_add_u64 v[34:35], v[26:27], 0, v[34:35]
	v_ashrrev_i32_e32 v33, 31, v32
	global_load_dword v23, v[34:35], off
	v_lshlrev_b64 v[34:35], 2, v[32:33]
	v_or_b32_e32 v34, v34, v20
	v_lshlrev_b64 v[36:37], 14, v[34:35]
	v_lshlrev_b64 v[34:35], 8, v[34:35]
	v_lshl_add_u64 v[34:35], v[12:13], 0, v[34:35]
	s_xor_b32 s0, s11, 0x7ffffffd
	global_load_dword v47, v[34:35], off
	v_add_u32_e32 v34, s0, v17
	s_add_i32 s0, s11, 2
	v_mov_b32_e32 v35, s0
	v_cndmask_b32_e64 v34, v34, v35, s[2:3]
	v_add_u32_e32 v34, v34, v19
	v_lshl_or_b32 v34, v34, 1, v21
	v_lshl_add_u64 v[36:37], v[26:27], 0, v[36:37]
	v_ashrrev_i32_e32 v35, 31, v34
	global_load_dword v46, v[36:37], off
	v_lshlrev_b64 v[36:37], 2, v[34:35]
	v_or_b32_e32 v36, v36, v20
	v_lshlrev_b64 v[38:39], 14, v[36:37]
	v_lshlrev_b64 v[36:37], 8, v[36:37]
	v_lshl_add_u64 v[36:37], v[12:13], 0, v[36:37]
	s_xor_b32 s0, s11, 0x7ffffffc
	global_load_dword v49, v[36:37], off
	v_add_u32_e32 v36, s0, v17
	s_add_i32 s0, s11, 3
	v_mov_b32_e32 v37, s0
	v_cndmask_b32_e64 v36, v36, v37, s[2:3]
	v_add_u32_e32 v36, v36, v19
	v_lshl_or_b32 v36, v36, 1, v21
	v_lshl_add_u64 v[38:39], v[26:27], 0, v[38:39]
	v_ashrrev_i32_e32 v37, 31, v36
	global_load_dword v48, v[38:39], off
	v_lshlrev_b64 v[38:39], 2, v[36:37]
	v_or_b32_e32 v38, v38, v20
	v_lshlrev_b64 v[40:41], 14, v[38:39]
	v_lshlrev_b64 v[38:39], 8, v[38:39]
	v_lshl_add_u64 v[38:39], v[12:13], 0, v[38:39]
	s_xor_b32 s0, s11, 0x7ffffffb
	global_load_dword v51, v[38:39], off
	v_add_u32_e32 v38, s0, v17
	s_add_i32 s0, s11, 4
	v_mov_b32_e32 v39, s0
	v_cndmask_b32_e64 v38, v38, v39, s[2:3]
	v_add_u32_e32 v38, v38, v19
	v_lshl_or_b32 v38, v38, 1, v21
	v_lshl_add_u64 v[40:41], v[26:27], 0, v[40:41]
	v_ashrrev_i32_e32 v39, 31, v38
	global_load_dword v50, v[40:41], off
	v_lshlrev_b64 v[40:41], 2, v[38:39]
	v_or_b32_e32 v40, v40, v20
	v_lshlrev_b64 v[42:43], 14, v[40:41]
	v_lshlrev_b64 v[40:41], 8, v[40:41]
	v_lshl_add_u64 v[40:41], v[12:13], 0, v[40:41]
	s_xor_b32 s0, s11, 0x7ffffffa
	global_load_dword v53, v[40:41], off
	v_add_u32_e32 v40, s0, v17
	s_add_i32 s0, s11, 5
	v_mov_b32_e32 v41, s0
	v_cndmask_b32_e64 v40, v40, v41, s[2:3]
	v_add_u32_e32 v40, v40, v19
	v_lshl_or_b32 v40, v40, 1, v21
	v_lshl_add_u64 v[42:43], v[26:27], 0, v[42:43]
	v_ashrrev_i32_e32 v41, 31, v40
	global_load_dword v52, v[42:43], off
	v_lshlrev_b64 v[42:43], 2, v[40:41]
	v_or_b32_e32 v42, v42, v20
	v_lshlrev_b64 v[54:55], 14, v[42:43]
	v_lshlrev_b64 v[42:43], 8, v[42:43]
	v_lshl_add_u64 v[42:43], v[12:13], 0, v[42:43]
	s_xor_b32 s0, s11, 0x7ffffff9
	global_load_dword v61, v[42:43], off
	v_add_u32_e32 v42, s0, v17
	s_add_i32 s0, s11, 6
	v_mov_b32_e32 v43, s0
	v_cndmask_b32_e64 v42, v42, v43, s[2:3]
	v_add_u32_e32 v42, v42, v19
	v_lshl_or_b32 v42, v42, 1, v21
	v_lshl_add_u64 v[54:55], v[26:27], 0, v[54:55]
	v_ashrrev_i32_e32 v43, 31, v42
	global_load_dword v60, v[54:55], off
	v_lshlrev_b64 v[54:55], 2, v[42:43]
	v_or_b32_e32 v54, v54, v20
	v_lshlrev_b64 v[56:57], 14, v[54:55]
	v_lshlrev_b64 v[54:55], 8, v[54:55]
	v_lshl_add_u64 v[54:55], v[12:13], 0, v[54:55]
	s_xor_b32 s0, s11, 0x7ffffff8
	global_load_dword v63, v[54:55], off
	v_add_u32_e32 v54, s0, v17
	s_add_i32 s0, s11, 7
	v_mov_b32_e32 v55, s0
	v_cndmask_b32_e64 v54, v54, v55, s[2:3]
	v_add_u32_e32 v54, v54, v19
	v_lshl_or_b32 v54, v54, 1, v21
	v_lshl_add_u64 v[56:57], v[26:27], 0, v[56:57]
	v_ashrrev_i32_e32 v55, 31, v54
	global_load_dword v62, v[56:57], off
	v_lshlrev_b64 v[56:57], 2, v[54:55]
	v_or_b32_e32 v56, v56, v20
	v_lshlrev_b64 v[58:59], 14, v[56:57]
	v_lshl_add_u64 v[58:59], v[26:27], 0, v[58:59]
	v_lshlrev_b64 v[56:57], 8, v[56:57]
	global_load_dword v58, v[58:59], off
	v_lshl_add_u64 v[56:57], v[12:13], 0, v[56:57]
	global_load_dword v56, v[56:57], off
	v_lshlrev_b64 v[30:31], 16, v[30:31]
	v_lshl_add_u64 v[30:31], v[28:29], 0, v[30:31]
	s_add_i32 s11, s11, 8
	v_add_u32_e32 v15, -8, v15
	v_mov_b32_e32 v71, s11
	v_cndmask_b32_e64 v71, v15, v71, s[2:3]
	v_add_u32_e32 v71, v71, v19
	v_lshl_or_b32 v78, v71, 1, v21
	v_ashrrev_i32_e32 v79, 31, v78
	v_lshlrev_b64 v[80:81], 2, v[78:79]
	v_or_b32_e32 v80, v80, v20
	v_lshlrev_b64 v[82:83], 14, v[80:81]
	v_lshlrev_b64 v[80:81], 8, v[80:81]
	v_lshl_add_u64 v[80:81], v[12:13], 0, v[80:81]
	s_xor_b32 s0, s11, 0x7ffffffe
	global_load_dword v93, v[80:81], off
	v_add_u32_e32 v80, s0, v17
	s_add_i32 s0, s11, 1
	v_mov_b32_e32 v81, s0
	v_cndmask_b32_e64 v80, v80, v81, s[2:3]
	v_add_u32_e32 v80, v80, v19
	v_lshl_or_b32 v80, v80, 1, v21
	v_lshl_add_u64 v[82:83], v[26:27], 0, v[82:83]
	v_ashrrev_i32_e32 v81, 31, v80
	global_load_dword v71, v[82:83], off
	v_lshlrev_b64 v[82:83], 2, v[80:81]
	v_or_b32_e32 v82, v82, v20
	v_lshlrev_b64 v[84:85], 14, v[82:83]
	v_lshlrev_b64 v[82:83], 8, v[82:83]
	v_lshl_add_u64 v[82:83], v[12:13], 0, v[82:83]
	s_xor_b32 s0, s11, 0x7ffffffd
	global_load_dword v95, v[82:83], off
	v_add_u32_e32 v82, s0, v17
	s_add_i32 s0, s11, 2
	v_mov_b32_e32 v83, s0
	v_cndmask_b32_e64 v82, v82, v83, s[2:3]
	v_add_u32_e32 v82, v82, v19
	v_lshl_or_b32 v82, v82, 1, v21
	v_lshl_add_u64 v[84:85], v[26:27], 0, v[84:85]
	v_ashrrev_i32_e32 v83, 31, v82
	global_load_dword v94, v[84:85], off
	v_lshlrev_b64 v[84:85], 2, v[82:83]
	v_or_b32_e32 v84, v84, v20
	v_lshlrev_b64 v[86:87], 14, v[84:85]
	v_lshlrev_b64 v[84:85], 8, v[84:85]
	v_lshl_add_u64 v[84:85], v[12:13], 0, v[84:85]
	s_xor_b32 s0, s11, 0x7ffffffc
	global_load_dword v97, v[84:85], off
	v_add_u32_e32 v84, s0, v17
	s_add_i32 s0, s11, 3
	v_mov_b32_e32 v85, s0
	v_cndmask_b32_e64 v84, v84, v85, s[2:3]
	v_add_u32_e32 v84, v84, v19
	v_lshl_or_b32 v84, v84, 1, v21
	v_lshl_add_u64 v[86:87], v[26:27], 0, v[86:87]
	v_ashrrev_i32_e32 v85, 31, v84
	global_load_dword v96, v[86:87], off
	v_lshlrev_b64 v[86:87], 2, v[84:85]
	v_or_b32_e32 v86, v86, v20
	v_lshlrev_b64 v[88:89], 14, v[86:87]
	v_lshlrev_b64 v[86:87], 8, v[86:87]
	v_lshl_add_u64 v[86:87], v[12:13], 0, v[86:87]
	s_xor_b32 s0, s11, 0x7ffffffb
	global_load_dword v99, v[86:87], off
	v_add_u32_e32 v86, s0, v17
	s_add_i32 s0, s11, 4
	v_mov_b32_e32 v87, s0
	v_cndmask_b32_e64 v86, v86, v87, s[2:3]
	v_add_u32_e32 v86, v86, v19
	v_lshl_or_b32 v86, v86, 1, v21
	v_lshl_add_u64 v[88:89], v[26:27], 0, v[88:89]
	v_ashrrev_i32_e32 v87, 31, v86
	global_load_dword v98, v[88:89], off
	v_lshlrev_b64 v[88:89], 2, v[86:87]
	v_or_b32_e32 v88, v88, v20
	v_lshlrev_b64 v[90:91], 14, v[88:89]
	v_lshlrev_b64 v[88:89], 8, v[88:89]
	v_lshl_add_u64 v[88:89], v[12:13], 0, v[88:89]
	s_xor_b32 s0, s11, 0x7ffffffa
	global_load_dword v101, v[88:89], off
	v_add_u32_e32 v88, s0, v17
	s_add_i32 s0, s11, 5
	v_mov_b32_e32 v89, s0
	v_cndmask_b32_e64 v88, v88, v89, s[2:3]
	v_add_u32_e32 v88, v88, v19
	v_lshl_or_b32 v88, v88, 1, v21
	v_lshl_add_u64 v[90:91], v[26:27], 0, v[90:91]
	v_ashrrev_i32_e32 v89, 31, v88
	global_load_dword v100, v[90:91], off
	v_lshlrev_b64 v[90:91], 2, v[88:89]
	v_or_b32_e32 v90, v90, v20
	v_lshlrev_b64 v[102:103], 14, v[90:91]
	v_lshlrev_b64 v[90:91], 8, v[90:91]
	v_lshl_add_u64 v[90:91], v[12:13], 0, v[90:91]
	s_xor_b32 s0, s11, 0x7ffffff9
	global_load_dword v109, v[90:91], off
	v_add_u32_e32 v90, s0, v17
	s_add_i32 s0, s11, 6
	v_mov_b32_e32 v91, s0
	v_cndmask_b32_e64 v90, v90, v91, s[2:3]
	v_add_u32_e32 v90, v90, v19
	v_lshl_or_b32 v90, v90, 1, v21
	v_lshl_add_u64 v[102:103], v[26:27], 0, v[102:103]
	v_ashrrev_i32_e32 v91, 31, v90
	global_load_dword v108, v[102:103], off
	v_lshlrev_b64 v[102:103], 2, v[90:91]
	v_or_b32_e32 v102, v102, v20
	v_lshlrev_b64 v[104:105], 14, v[102:103]
	v_lshlrev_b64 v[102:103], 8, v[102:103]
	v_lshl_add_u64 v[102:103], v[12:13], 0, v[102:103]
	s_xor_b32 s0, s11, 0x7ffffff8
	global_load_dword v111, v[102:103], off
	v_add_u32_e32 v102, s0, v17
	s_add_i32 s0, s11, 7
	v_mov_b32_e32 v103, s0
	v_cndmask_b32_e64 v102, v102, v103, s[2:3]
	v_add_u32_e32 v102, v102, v19
	v_lshl_or_b32 v102, v102, 1, v21
	v_lshl_add_u64 v[104:105], v[26:27], 0, v[104:105]
	v_ashrrev_i32_e32 v103, 31, v102
	global_load_dword v110, v[104:105], off
	v_lshlrev_b64 v[104:105], 2, v[102:103]
	v_or_b32_e32 v104, v104, v20
	v_lshlrev_b64 v[106:107], 14, v[104:105]
	v_lshl_add_u64 v[106:107], v[26:27], 0, v[106:107]
	v_lshlrev_b64 v[104:105], 8, v[104:105]
	global_load_dword v106, v[106:107], off
	v_lshl_add_u64 v[104:105], v[12:13], 0, v[104:105]
	global_load_dword v104, v[104:105], off
	v_lshlrev_b64 v[78:79], 16, v[78:79]
	v_lshl_add_u64 v[78:79], v[28:29], 0, v[78:79]
	s_add_i32 s11, s11, 8
	v_add_u32_e32 v15, -8, v15
	v_mov_b32_e32 v119, s11
	v_cndmask_b32_e64 v119, v15, v119, s[2:3]
	v_add_u32_e32 v119, v119, v19
	v_lshl_or_b32 v126, v119, 1, v21
	v_ashrrev_i32_e32 v127, 31, v126
	v_lshlrev_b64 v[128:129], 2, v[126:127]
	v_or_b32_e32 v128, v128, v20
	v_lshlrev_b64 v[130:131], 14, v[128:129]
	v_lshlrev_b64 v[128:129], 8, v[128:129]
	v_lshl_add_u64 v[128:129], v[12:13], 0, v[128:129]
	s_xor_b32 s0, s11, 0x7ffffffe
	global_load_dword v141, v[128:129], off
	v_add_u32_e32 v128, s0, v17
	s_add_i32 s0, s11, 1
	v_mov_b32_e32 v129, s0
	v_cndmask_b32_e64 v128, v128, v129, s[2:3]
	v_add_u32_e32 v128, v128, v19
	v_lshl_or_b32 v128, v128, 1, v21
	v_lshl_add_u64 v[130:131], v[26:27], 0, v[130:131]
	v_ashrrev_i32_e32 v129, 31, v128
	global_load_dword v119, v[130:131], off
	v_lshlrev_b64 v[130:131], 2, v[128:129]
	v_or_b32_e32 v130, v130, v20
	v_lshlrev_b64 v[132:133], 14, v[130:131]
	v_lshlrev_b64 v[130:131], 8, v[130:131]
	v_lshl_add_u64 v[130:131], v[12:13], 0, v[130:131]
	s_xor_b32 s0, s11, 0x7ffffffd
	global_load_dword v143, v[130:131], off
	v_add_u32_e32 v130, s0, v17
	s_add_i32 s0, s11, 2
	v_mov_b32_e32 v131, s0
	v_cndmask_b32_e64 v130, v130, v131, s[2:3]
	v_add_u32_e32 v130, v130, v19
	v_lshl_or_b32 v130, v130, 1, v21
	v_lshl_add_u64 v[132:133], v[26:27], 0, v[132:133]
	v_ashrrev_i32_e32 v131, 31, v130
	global_load_dword v142, v[132:133], off
	v_lshlrev_b64 v[132:133], 2, v[130:131]
	v_or_b32_e32 v132, v132, v20
	v_lshlrev_b64 v[134:135], 14, v[132:133]
	v_lshlrev_b64 v[132:133], 8, v[132:133]
	v_lshl_add_u64 v[132:133], v[12:13], 0, v[132:133]
	s_xor_b32 s0, s11, 0x7ffffffc
	global_load_dword v145, v[132:133], off
	v_add_u32_e32 v132, s0, v17
	s_add_i32 s0, s11, 3
	v_mov_b32_e32 v133, s0
	v_cndmask_b32_e64 v132, v132, v133, s[2:3]
	v_add_u32_e32 v132, v132, v19
	v_lshl_or_b32 v132, v132, 1, v21
	v_lshl_add_u64 v[134:135], v[26:27], 0, v[134:135]
	v_ashrrev_i32_e32 v133, 31, v132
	global_load_dword v144, v[134:135], off
	v_lshlrev_b64 v[134:135], 2, v[132:133]
	v_or_b32_e32 v134, v134, v20
	v_lshlrev_b64 v[136:137], 14, v[134:135]
	v_lshlrev_b64 v[134:135], 8, v[134:135]
	v_lshl_add_u64 v[134:135], v[12:13], 0, v[134:135]
	s_xor_b32 s0, s11, 0x7ffffffb
	global_load_dword v147, v[134:135], off
	v_add_u32_e32 v134, s0, v17
	s_add_i32 s0, s11, 4
	v_mov_b32_e32 v135, s0
	v_cndmask_b32_e64 v134, v134, v135, s[2:3]
	v_add_u32_e32 v134, v134, v19
	v_lshl_or_b32 v134, v134, 1, v21
	v_lshl_add_u64 v[136:137], v[26:27], 0, v[136:137]
	v_ashrrev_i32_e32 v135, 31, v134
	global_load_dword v146, v[136:137], off
	v_lshlrev_b64 v[136:137], 2, v[134:135]
	v_or_b32_e32 v136, v136, v20
	v_lshlrev_b64 v[138:139], 14, v[136:137]
	v_lshlrev_b64 v[136:137], 8, v[136:137]
	v_lshl_add_u64 v[136:137], v[12:13], 0, v[136:137]
	s_xor_b32 s0, s11, 0x7ffffffa
	global_load_dword v149, v[136:137], off
	v_add_u32_e32 v136, s0, v17
	s_add_i32 s0, s11, 5
	v_mov_b32_e32 v137, s0
	v_cndmask_b32_e64 v136, v136, v137, s[2:3]
	v_add_u32_e32 v136, v136, v19
	v_lshl_or_b32 v136, v136, 1, v21
	v_lshl_add_u64 v[138:139], v[26:27], 0, v[138:139]
	v_ashrrev_i32_e32 v137, 31, v136
	global_load_dword v148, v[138:139], off
	v_lshlrev_b64 v[138:139], 2, v[136:137]
	v_or_b32_e32 v138, v138, v20
	v_lshlrev_b64 v[150:151], 14, v[138:139]
	v_lshlrev_b64 v[138:139], 8, v[138:139]
	v_lshl_add_u64 v[138:139], v[12:13], 0, v[138:139]
	s_xor_b32 s0, s11, 0x7ffffff9
	global_load_dword v157, v[138:139], off
	v_add_u32_e32 v138, s0, v17
	s_add_i32 s0, s11, 6
	v_mov_b32_e32 v139, s0
	v_cndmask_b32_e64 v138, v138, v139, s[2:3]
	v_add_u32_e32 v138, v138, v19
	v_lshl_or_b32 v138, v138, 1, v21
	v_lshl_add_u64 v[150:151], v[26:27], 0, v[150:151]
	v_ashrrev_i32_e32 v139, 31, v138
	global_load_dword v156, v[150:151], off
	v_lshlrev_b64 v[150:151], 2, v[138:139]
	v_or_b32_e32 v150, v150, v20
	v_lshlrev_b64 v[152:153], 14, v[150:151]
	v_lshlrev_b64 v[150:151], 8, v[150:151]
	v_lshl_add_u64 v[150:151], v[12:13], 0, v[150:151]
	s_xor_b32 s0, s11, 0x7ffffff8
	global_load_dword v159, v[150:151], off
	v_add_u32_e32 v150, s0, v17
	s_add_i32 s0, s11, 7
	v_mov_b32_e32 v151, s0
	v_cndmask_b32_e64 v150, v150, v151, s[2:3]
	v_add_u32_e32 v150, v150, v19
	v_lshl_or_b32 v150, v150, 1, v21
	v_lshl_add_u64 v[152:153], v[26:27], 0, v[152:153]
	v_ashrrev_i32_e32 v151, 31, v150
	global_load_dword v158, v[152:153], off
	v_lshlrev_b64 v[152:153], 2, v[150:151]
	v_or_b32_e32 v152, v152, v20
	v_lshlrev_b64 v[154:155], 14, v[152:153]
	v_lshl_add_u64 v[154:155], v[26:27], 0, v[154:155]
	v_lshlrev_b64 v[152:153], 8, v[152:153]
	global_load_dword v154, v[154:155], off
	v_lshl_add_u64 v[152:153], v[12:13], 0, v[152:153]
	global_load_dword v152, v[152:153], off
	v_lshlrev_b64 v[126:127], 16, v[126:127]
	v_lshl_add_u64 v[126:127], v[28:29], 0, v[126:127]
	s_add_i32 s11, s11, 8
	v_add_u32_e32 v15, -8, v15
	v_mov_b32_e32 v167, s11
	v_cndmask_b32_e64 v167, v15, v167, s[2:3]
	v_add_u32_e32 v167, v167, v19
	v_lshl_or_b32 v174, v167, 1, v21
	v_ashrrev_i32_e32 v175, 31, v174
	v_lshlrev_b64 v[176:177], 2, v[174:175]
	v_or_b32_e32 v176, v176, v20
	v_lshlrev_b64 v[178:179], 14, v[176:177]
	v_lshlrev_b64 v[176:177], 8, v[176:177]
	v_lshl_add_u64 v[176:177], v[12:13], 0, v[176:177]
	s_xor_b32 s0, s11, 0x7ffffffe
	global_load_dword v189, v[176:177], off
	v_add_u32_e32 v176, s0, v17
	s_add_i32 s0, s11, 1
	v_mov_b32_e32 v177, s0
	v_cndmask_b32_e64 v176, v176, v177, s[2:3]
	v_add_u32_e32 v176, v176, v19
	v_lshl_or_b32 v176, v176, 1, v21
	v_lshl_add_u64 v[178:179], v[26:27], 0, v[178:179]
	v_ashrrev_i32_e32 v177, 31, v176
	global_load_dword v167, v[178:179], off
	v_lshlrev_b64 v[178:179], 2, v[176:177]
	v_or_b32_e32 v178, v178, v20
	v_lshlrev_b64 v[180:181], 14, v[178:179]
	v_lshlrev_b64 v[178:179], 8, v[178:179]
	v_lshl_add_u64 v[178:179], v[12:13], 0, v[178:179]
	s_xor_b32 s0, s11, 0x7ffffffd
	global_load_dword v191, v[178:179], off
	v_add_u32_e32 v178, s0, v17
	s_add_i32 s0, s11, 2
	v_mov_b32_e32 v179, s0
	v_cndmask_b32_e64 v178, v178, v179, s[2:3]
	v_add_u32_e32 v178, v178, v19
	v_lshl_or_b32 v178, v178, 1, v21
	v_lshl_add_u64 v[180:181], v[26:27], 0, v[180:181]
	v_ashrrev_i32_e32 v179, 31, v178
	global_load_dword v190, v[180:181], off
	v_lshlrev_b64 v[180:181], 2, v[178:179]
	v_or_b32_e32 v180, v180, v20
	v_lshlrev_b64 v[182:183], 14, v[180:181]
	v_lshlrev_b64 v[180:181], 8, v[180:181]
	v_lshl_add_u64 v[180:181], v[12:13], 0, v[180:181]
	s_xor_b32 s0, s11, 0x7ffffffc
	global_load_dword v193, v[180:181], off
	v_add_u32_e32 v180, s0, v17
	s_add_i32 s0, s11, 3
	v_mov_b32_e32 v181, s0
	v_cndmask_b32_e64 v180, v180, v181, s[2:3]
	v_add_u32_e32 v180, v180, v19
	v_lshl_or_b32 v180, v180, 1, v21
	v_lshl_add_u64 v[182:183], v[26:27], 0, v[182:183]
	v_ashrrev_i32_e32 v181, 31, v180
	global_load_dword v192, v[182:183], off
	v_lshlrev_b64 v[182:183], 2, v[180:181]
	v_or_b32_e32 v182, v182, v20
	v_lshlrev_b64 v[184:185], 14, v[182:183]
	v_lshlrev_b64 v[182:183], 8, v[182:183]
	v_lshl_add_u64 v[182:183], v[12:13], 0, v[182:183]
	s_xor_b32 s0, s11, 0x7ffffffb
	global_load_dword v195, v[182:183], off
	v_add_u32_e32 v182, s0, v17
	s_add_i32 s0, s11, 4
	v_mov_b32_e32 v183, s0
	v_cndmask_b32_e64 v182, v182, v183, s[2:3]
	v_add_u32_e32 v182, v182, v19
	v_lshl_or_b32 v182, v182, 1, v21
	v_lshl_add_u64 v[184:185], v[26:27], 0, v[184:185]
	v_ashrrev_i32_e32 v183, 31, v182
	global_load_dword v194, v[184:185], off
	v_lshlrev_b64 v[184:185], 2, v[182:183]
	v_or_b32_e32 v184, v184, v20
	v_lshlrev_b64 v[186:187], 14, v[184:185]
	v_lshlrev_b64 v[184:185], 8, v[184:185]
	v_lshl_add_u64 v[184:185], v[12:13], 0, v[184:185]
	s_xor_b32 s0, s11, 0x7ffffffa
	global_load_dword v197, v[184:185], off
	v_add_u32_e32 v184, s0, v17
	s_add_i32 s0, s11, 5
	v_mov_b32_e32 v185, s0
	v_cndmask_b32_e64 v184, v184, v185, s[2:3]
	v_add_u32_e32 v184, v184, v19
	v_lshl_or_b32 v184, v184, 1, v21
	v_lshl_add_u64 v[186:187], v[26:27], 0, v[186:187]
	v_ashrrev_i32_e32 v185, 31, v184
	global_load_dword v196, v[186:187], off
	v_lshlrev_b64 v[186:187], 2, v[184:185]
	v_or_b32_e32 v186, v186, v20
	v_lshlrev_b64 v[198:199], 14, v[186:187]
	v_lshlrev_b64 v[186:187], 8, v[186:187]
	v_lshl_add_u64 v[186:187], v[12:13], 0, v[186:187]
	s_xor_b32 s0, s11, 0x7ffffff9
	global_load_dword v205, v[186:187], off
	v_add_u32_e32 v186, s0, v17
	s_add_i32 s0, s11, 6
	v_mov_b32_e32 v187, s0
	v_cndmask_b32_e64 v186, v186, v187, s[2:3]
	v_add_u32_e32 v186, v186, v19
	v_lshl_or_b32 v186, v186, 1, v21
	v_lshl_add_u64 v[198:199], v[26:27], 0, v[198:199]
	v_ashrrev_i32_e32 v187, 31, v186
	global_load_dword v204, v[198:199], off
	v_lshlrev_b64 v[198:199], 2, v[186:187]
	v_or_b32_e32 v198, v198, v20
	v_lshlrev_b64 v[200:201], 14, v[198:199]
	v_lshlrev_b64 v[198:199], 8, v[198:199]
	v_lshl_add_u64 v[198:199], v[12:13], 0, v[198:199]
	s_xor_b32 s0, s11, 0x7ffffff8
	global_load_dword v207, v[198:199], off
	v_add_u32_e32 v198, s0, v17
	s_add_i32 s0, s11, 7
	v_mov_b32_e32 v199, s0
	v_cndmask_b32_e64 v198, v198, v199, s[2:3]
	v_add_u32_e32 v198, v198, v19
	v_lshl_or_b32 v198, v198, 1, v21
	v_lshl_add_u64 v[200:201], v[26:27], 0, v[200:201]
	v_ashrrev_i32_e32 v199, 31, v198
	global_load_dword v206, v[200:201], off
	v_lshlrev_b64 v[200:201], 2, v[198:199]
	v_or_b32_e32 v200, v200, v20
	v_lshlrev_b64 v[202:203], 14, v[200:201]
	v_lshl_add_u64 v[202:203], v[26:27], 0, v[202:203]
	v_lshlrev_b64 v[200:201], 8, v[200:201]
	global_load_dword v202, v[202:203], off
	v_lshl_add_u64 v[200:201], v[12:13], 0, v[200:201]
	global_load_dword v200, v[200:201], off
	v_lshlrev_b64 v[174:175], 16, v[174:175]
	v_lshl_add_u64 v[174:175], v[28:29], 0, v[174:175]
	s_add_i32 s11, s11, 8
	v_add_u32_e32 v15, -8, v15
	s_waitcnt vmcnt(48)
	global_store_dword v[30:31], v44, off
	v_lshlrev_b64 v[30:31], 16, v[32:33]
	v_fmac_f32_e32 v23, v44, v45
	v_lshl_add_u64 v[30:31], v[28:29], 0, v[30:31]
	global_store_dword v[30:31], v23, off
	v_lshlrev_b64 v[30:31], 16, v[34:35]
	v_fmac_f32_e32 v46, v23, v47
	v_lshl_add_u64 v[30:31], v[28:29], 0, v[30:31]
	global_store_dword v[30:31], v46, off
	v_lshlrev_b64 v[30:31], 16, v[36:37]
	v_fmac_f32_e32 v48, v46, v49
	v_lshl_add_u64 v[30:31], v[28:29], 0, v[30:31]
	global_store_dword v[30:31], v48, off
	v_lshlrev_b64 v[30:31], 16, v[38:39]
	v_lshl_add_u64 v[30:31], v[28:29], 0, v[30:31]
	v_fmac_f32_e32 v50, v48, v51
	global_store_dword v[30:31], v50, off
	v_lshlrev_b64 v[30:31], 16, v[40:41]
	v_lshl_add_u64 v[30:31], v[28:29], 0, v[30:31]
	v_fmac_f32_e32 v52, v50, v53
	global_store_dword v[30:31], v52, off
	v_lshlrev_b64 v[30:31], 16, v[42:43]
	v_lshl_add_u64 v[30:31], v[28:29], 0, v[30:31]
	v_fmac_f32_e32 v60, v52, v61
	global_store_dword v[30:31], v60, off
	v_lshlrev_b64 v[30:31], 16, v[54:55]
	v_lshl_add_u64 v[30:31], v[28:29], 0, v[30:31]
	v_fmac_f32_e32 v62, v60, v63
	global_store_dword v[30:31], v62, off
	v_mov_b32_e32 v44, v58
	v_fmac_f32_e32 v44, v62, v56
	s_waitcnt vmcnt(40)
	global_store_dword v[78:79], v44, off
	v_lshlrev_b64 v[78:79], 16, v[80:81]
	v_fmac_f32_e32 v71, v44, v93
	v_lshl_add_u64 v[78:79], v[28:29], 0, v[78:79]
	global_store_dword v[78:79], v71, off
	v_lshlrev_b64 v[78:79], 16, v[82:83]
	v_fmac_f32_e32 v94, v71, v95
	v_lshl_add_u64 v[78:79], v[28:29], 0, v[78:79]
	global_store_dword v[78:79], v94, off
	v_lshlrev_b64 v[78:79], 16, v[84:85]
	v_fmac_f32_e32 v96, v94, v97
	v_lshl_add_u64 v[78:79], v[28:29], 0, v[78:79]
	global_store_dword v[78:79], v96, off
	v_lshlrev_b64 v[78:79], 16, v[86:87]
	v_lshl_add_u64 v[78:79], v[28:29], 0, v[78:79]
	v_fmac_f32_e32 v98, v96, v99
	global_store_dword v[78:79], v98, off
	v_lshlrev_b64 v[78:79], 16, v[88:89]
	v_lshl_add_u64 v[78:79], v[28:29], 0, v[78:79]
	v_fmac_f32_e32 v100, v98, v101
	global_store_dword v[78:79], v100, off
	v_lshlrev_b64 v[78:79], 16, v[90:91]
	v_lshl_add_u64 v[78:79], v[28:29], 0, v[78:79]
	v_fmac_f32_e32 v108, v100, v109
	global_store_dword v[78:79], v108, off
	v_lshlrev_b64 v[78:79], 16, v[102:103]
	v_lshl_add_u64 v[78:79], v[28:29], 0, v[78:79]
	v_fmac_f32_e32 v110, v108, v111
	global_store_dword v[78:79], v110, off
	v_mov_b32_e32 v44, v106
	v_fmac_f32_e32 v44, v110, v104
	s_waitcnt vmcnt(32)
	global_store_dword v[126:127], v44, off
	v_lshlrev_b64 v[126:127], 16, v[128:129]
	v_fmac_f32_e32 v119, v44, v141
	v_lshl_add_u64 v[126:127], v[28:29], 0, v[126:127]
	global_store_dword v[126:127], v119, off
	v_lshlrev_b64 v[126:127], 16, v[130:131]
	v_fmac_f32_e32 v142, v119, v143
	v_lshl_add_u64 v[126:127], v[28:29], 0, v[126:127]
	global_store_dword v[126:127], v142, off
	v_lshlrev_b64 v[126:127], 16, v[132:133]
	v_fmac_f32_e32 v144, v142, v145
	v_lshl_add_u64 v[126:127], v[28:29], 0, v[126:127]
	global_store_dword v[126:127], v144, off
	v_lshlrev_b64 v[126:127], 16, v[134:135]
	v_lshl_add_u64 v[126:127], v[28:29], 0, v[126:127]
	v_fmac_f32_e32 v146, v144, v147
	global_store_dword v[126:127], v146, off
	v_lshlrev_b64 v[126:127], 16, v[136:137]
	v_lshl_add_u64 v[126:127], v[28:29], 0, v[126:127]
	v_fmac_f32_e32 v148, v146, v149
	global_store_dword v[126:127], v148, off
	v_lshlrev_b64 v[126:127], 16, v[138:139]
	v_lshl_add_u64 v[126:127], v[28:29], 0, v[126:127]
	v_fmac_f32_e32 v156, v148, v157
	global_store_dword v[126:127], v156, off
	v_lshlrev_b64 v[126:127], 16, v[150:151]
	v_lshl_add_u64 v[126:127], v[28:29], 0, v[126:127]
	v_fmac_f32_e32 v158, v156, v159
	global_store_dword v[126:127], v158, off
	v_mov_b32_e32 v44, v154
	v_fmac_f32_e32 v44, v158, v152
	s_waitcnt vmcnt(24)
	global_store_dword v[174:175], v44, off
	v_lshlrev_b64 v[174:175], 16, v[176:177]
	v_fmac_f32_e32 v167, v44, v189
	v_lshl_add_u64 v[174:175], v[28:29], 0, v[174:175]
	global_store_dword v[174:175], v167, off
	v_lshlrev_b64 v[174:175], 16, v[178:179]
	v_fmac_f32_e32 v190, v167, v191
	v_lshl_add_u64 v[174:175], v[28:29], 0, v[174:175]
	global_store_dword v[174:175], v190, off
	v_lshlrev_b64 v[174:175], 16, v[180:181]
	v_fmac_f32_e32 v192, v190, v193
	v_lshl_add_u64 v[174:175], v[28:29], 0, v[174:175]
	global_store_dword v[174:175], v192, off
	v_lshlrev_b64 v[174:175], 16, v[182:183]
	v_lshl_add_u64 v[174:175], v[28:29], 0, v[174:175]
	v_fmac_f32_e32 v194, v192, v195
	global_store_dword v[174:175], v194, off
	v_lshlrev_b64 v[174:175], 16, v[184:185]
	v_lshl_add_u64 v[174:175], v[28:29], 0, v[174:175]
	v_fmac_f32_e32 v196, v194, v197
	global_store_dword v[174:175], v196, off
	v_lshlrev_b64 v[174:175], 16, v[186:187]
	v_lshl_add_u64 v[174:175], v[28:29], 0, v[174:175]
	v_fmac_f32_e32 v204, v196, v205
	global_store_dword v[174:175], v204, off
	v_lshlrev_b64 v[174:175], 16, v[198:199]
	v_lshl_add_u64 v[174:175], v[28:29], 0, v[174:175]
	v_fmac_f32_e32 v206, v204, v207
	global_store_dword v[174:175], v206, off
	v_mov_b32_e32 v44, v202
	v_fmac_f32_e32 v44, v206, v200
	v_mov_b32_e32 v23, s11
	v_cndmask_b32_e64 v23, v15, v23, s[2:3]
	v_add_u32_e32 v23, v23, v19
	v_lshl_or_b32 v30, v23, 1, v21
	v_ashrrev_i32_e32 v31, 31, v30
	v_lshlrev_b64 v[32:33], 2, v[30:31]
	v_or_b32_e32 v32, v32, v20
	v_lshlrev_b64 v[34:35], 14, v[32:33]
	v_lshlrev_b64 v[32:33], 8, v[32:33]
	v_lshl_add_u64 v[32:33], v[12:13], 0, v[32:33]
	s_xor_b32 s0, s11, 0x7ffffffe
	global_load_dword v45, v[32:33], off
	v_add_u32_e32 v32, s0, v17
	s_add_i32 s0, s11, 1
	v_mov_b32_e32 v33, s0
	v_cndmask_b32_e64 v32, v32, v33, s[2:3]
	v_add_u32_e32 v32, v32, v19
	v_lshl_or_b32 v32, v32, 1, v21
	v_lshl_add_u64 v[34:35], v[26:27], 0, v[34:35]
	v_ashrrev_i32_e32 v33, 31, v32
	global_load_dword v23, v[34:35], off
	v_lshlrev_b64 v[34:35], 2, v[32:33]
	v_or_b32_e32 v34, v34, v20
	v_lshlrev_b64 v[36:37], 14, v[34:35]
	v_lshlrev_b64 v[34:35], 8, v[34:35]
	v_lshl_add_u64 v[34:35], v[12:13], 0, v[34:35]
	s_xor_b32 s0, s11, 0x7ffffffd
	global_load_dword v47, v[34:35], off
	v_add_u32_e32 v34, s0, v17
	s_add_i32 s0, s11, 2
	v_mov_b32_e32 v35, s0
	v_cndmask_b32_e64 v34, v34, v35, s[2:3]
	v_add_u32_e32 v34, v34, v19
	v_lshl_or_b32 v34, v34, 1, v21
	v_lshl_add_u64 v[36:37], v[26:27], 0, v[36:37]
	v_ashrrev_i32_e32 v35, 31, v34
	global_load_dword v46, v[36:37], off
	v_lshlrev_b64 v[36:37], 2, v[34:35]
	v_or_b32_e32 v36, v36, v20
	v_lshlrev_b64 v[38:39], 14, v[36:37]
	v_lshlrev_b64 v[36:37], 8, v[36:37]
	v_lshl_add_u64 v[36:37], v[12:13], 0, v[36:37]
	s_xor_b32 s0, s11, 0x7ffffffc
	global_load_dword v49, v[36:37], off
	v_add_u32_e32 v36, s0, v17
	s_add_i32 s0, s11, 3
	v_mov_b32_e32 v37, s0
	v_cndmask_b32_e64 v36, v36, v37, s[2:3]
	v_add_u32_e32 v36, v36, v19
	v_lshl_or_b32 v36, v36, 1, v21
	v_lshl_add_u64 v[38:39], v[26:27], 0, v[38:39]
	v_ashrrev_i32_e32 v37, 31, v36
	global_load_dword v48, v[38:39], off
	v_lshlrev_b64 v[38:39], 2, v[36:37]
	v_or_b32_e32 v38, v38, v20
	v_lshlrev_b64 v[40:41], 14, v[38:39]
	v_lshlrev_b64 v[38:39], 8, v[38:39]
	v_lshl_add_u64 v[38:39], v[12:13], 0, v[38:39]
	s_xor_b32 s0, s11, 0x7ffffffb
	global_load_dword v51, v[38:39], off
	v_add_u32_e32 v38, s0, v17
	s_add_i32 s0, s11, 4
	v_mov_b32_e32 v39, s0
	v_cndmask_b32_e64 v38, v38, v39, s[2:3]
	v_add_u32_e32 v38, v38, v19
	v_lshl_or_b32 v38, v38, 1, v21
	v_lshl_add_u64 v[40:41], v[26:27], 0, v[40:41]
	v_ashrrev_i32_e32 v39, 31, v38
	global_load_dword v50, v[40:41], off
	v_lshlrev_b64 v[40:41], 2, v[38:39]
	v_or_b32_e32 v40, v40, v20
	v_lshlrev_b64 v[42:43], 14, v[40:41]
	v_lshlrev_b64 v[40:41], 8, v[40:41]
	v_lshl_add_u64 v[40:41], v[12:13], 0, v[40:41]
	s_xor_b32 s0, s11, 0x7ffffffa
	global_load_dword v53, v[40:41], off
	v_add_u32_e32 v40, s0, v17
	s_add_i32 s0, s11, 5
	v_mov_b32_e32 v41, s0
	v_cndmask_b32_e64 v40, v40, v41, s[2:3]
	v_add_u32_e32 v40, v40, v19
	v_lshl_or_b32 v40, v40, 1, v21
	v_lshl_add_u64 v[42:43], v[26:27], 0, v[42:43]
	v_ashrrev_i32_e32 v41, 31, v40
	global_load_dword v52, v[42:43], off
	v_lshlrev_b64 v[42:43], 2, v[40:41]
	v_or_b32_e32 v42, v42, v20
	v_lshlrev_b64 v[54:55], 14, v[42:43]
	v_lshlrev_b64 v[42:43], 8, v[42:43]
	v_lshl_add_u64 v[42:43], v[12:13], 0, v[42:43]
	s_xor_b32 s0, s11, 0x7ffffff9
	global_load_dword v61, v[42:43], off
	v_add_u32_e32 v42, s0, v17
	s_add_i32 s0, s11, 6
	v_mov_b32_e32 v43, s0
	v_cndmask_b32_e64 v42, v42, v43, s[2:3]
	v_add_u32_e32 v42, v42, v19
	v_lshl_or_b32 v42, v42, 1, v21
	v_lshl_add_u64 v[54:55], v[26:27], 0, v[54:55]
	v_ashrrev_i32_e32 v43, 31, v42
	global_load_dword v60, v[54:55], off
	v_lshlrev_b64 v[54:55], 2, v[42:43]
	v_or_b32_e32 v54, v54, v20
	v_lshlrev_b64 v[56:57], 14, v[54:55]
	v_lshlrev_b64 v[54:55], 8, v[54:55]
	v_lshl_add_u64 v[54:55], v[12:13], 0, v[54:55]
	s_xor_b32 s0, s11, 0x7ffffff8
	global_load_dword v63, v[54:55], off
	v_add_u32_e32 v54, s0, v17
	s_add_i32 s0, s11, 7
	v_mov_b32_e32 v55, s0
	v_cndmask_b32_e64 v54, v54, v55, s[2:3]
	v_add_u32_e32 v54, v54, v19
	v_lshl_or_b32 v54, v54, 1, v21
	v_lshl_add_u64 v[56:57], v[26:27], 0, v[56:57]
	v_ashrrev_i32_e32 v55, 31, v54
	global_load_dword v62, v[56:57], off
	v_lshlrev_b64 v[56:57], 2, v[54:55]
	v_or_b32_e32 v56, v56, v20
	v_lshlrev_b64 v[58:59], 14, v[56:57]
	v_lshl_add_u64 v[58:59], v[26:27], 0, v[58:59]
	v_lshlrev_b64 v[56:57], 8, v[56:57]
	global_load_dword v58, v[58:59], off
	v_lshl_add_u64 v[56:57], v[12:13], 0, v[56:57]
	global_load_dword v56, v[56:57], off
	v_lshlrev_b64 v[30:31], 16, v[30:31]
	v_lshl_add_u64 v[30:31], v[28:29], 0, v[30:31]
	s_add_i32 s11, s11, 8
	v_add_u32_e32 v15, -8, v15
	v_mov_b32_e32 v71, s11
	v_cndmask_b32_e64 v71, v15, v71, s[2:3]
	v_add_u32_e32 v71, v71, v19
	v_lshl_or_b32 v78, v71, 1, v21
	v_ashrrev_i32_e32 v79, 31, v78
	v_lshlrev_b64 v[80:81], 2, v[78:79]
	v_or_b32_e32 v80, v80, v20
	v_lshlrev_b64 v[82:83], 14, v[80:81]
	v_lshlrev_b64 v[80:81], 8, v[80:81]
	v_lshl_add_u64 v[80:81], v[12:13], 0, v[80:81]
	s_xor_b32 s0, s11, 0x7ffffffe
	global_load_dword v93, v[80:81], off
	v_add_u32_e32 v80, s0, v17
	s_add_i32 s0, s11, 1
	v_mov_b32_e32 v81, s0
	v_cndmask_b32_e64 v80, v80, v81, s[2:3]
	v_add_u32_e32 v80, v80, v19
	v_lshl_or_b32 v80, v80, 1, v21
	v_lshl_add_u64 v[82:83], v[26:27], 0, v[82:83]
	v_ashrrev_i32_e32 v81, 31, v80
	global_load_dword v71, v[82:83], off
	v_lshlrev_b64 v[82:83], 2, v[80:81]
	v_or_b32_e32 v82, v82, v20
	v_lshlrev_b64 v[84:85], 14, v[82:83]
	v_lshlrev_b64 v[82:83], 8, v[82:83]
	v_lshl_add_u64 v[82:83], v[12:13], 0, v[82:83]
	s_xor_b32 s0, s11, 0x7ffffffd
	global_load_dword v95, v[82:83], off
	v_add_u32_e32 v82, s0, v17
	s_add_i32 s0, s11, 2
	v_mov_b32_e32 v83, s0
	v_cndmask_b32_e64 v82, v82, v83, s[2:3]
	v_add_u32_e32 v82, v82, v19
	v_lshl_or_b32 v82, v82, 1, v21
	v_lshl_add_u64 v[84:85], v[26:27], 0, v[84:85]
	v_ashrrev_i32_e32 v83, 31, v82
	global_load_dword v94, v[84:85], off
	v_lshlrev_b64 v[84:85], 2, v[82:83]
	v_or_b32_e32 v84, v84, v20
	v_lshlrev_b64 v[86:87], 14, v[84:85]
	v_lshlrev_b64 v[84:85], 8, v[84:85]
	v_lshl_add_u64 v[84:85], v[12:13], 0, v[84:85]
	s_xor_b32 s0, s11, 0x7ffffffc
	global_load_dword v97, v[84:85], off
	v_add_u32_e32 v84, s0, v17
	s_add_i32 s0, s11, 3
	v_mov_b32_e32 v85, s0
	v_cndmask_b32_e64 v84, v84, v85, s[2:3]
	v_add_u32_e32 v84, v84, v19
	v_lshl_or_b32 v84, v84, 1, v21
	v_lshl_add_u64 v[86:87], v[26:27], 0, v[86:87]
	v_ashrrev_i32_e32 v85, 31, v84
	global_load_dword v96, v[86:87], off
	v_lshlrev_b64 v[86:87], 2, v[84:85]
	v_or_b32_e32 v86, v86, v20
	v_lshlrev_b64 v[88:89], 14, v[86:87]
	v_lshlrev_b64 v[86:87], 8, v[86:87]
	v_lshl_add_u64 v[86:87], v[12:13], 0, v[86:87]
	s_xor_b32 s0, s11, 0x7ffffffb
	global_load_dword v99, v[86:87], off
	v_add_u32_e32 v86, s0, v17
	s_add_i32 s0, s11, 4
	v_mov_b32_e32 v87, s0
	v_cndmask_b32_e64 v86, v86, v87, s[2:3]
	v_add_u32_e32 v86, v86, v19
	v_lshl_or_b32 v86, v86, 1, v21
	v_lshl_add_u64 v[88:89], v[26:27], 0, v[88:89]
	v_ashrrev_i32_e32 v87, 31, v86
	global_load_dword v98, v[88:89], off
	v_lshlrev_b64 v[88:89], 2, v[86:87]
	v_or_b32_e32 v88, v88, v20
	v_lshlrev_b64 v[90:91], 14, v[88:89]
	v_lshlrev_b64 v[88:89], 8, v[88:89]
	v_lshl_add_u64 v[88:89], v[12:13], 0, v[88:89]
	s_xor_b32 s0, s11, 0x7ffffffa
	global_load_dword v101, v[88:89], off
	v_add_u32_e32 v88, s0, v17
	s_add_i32 s0, s11, 5
	v_mov_b32_e32 v89, s0
	v_cndmask_b32_e64 v88, v88, v89, s[2:3]
	v_add_u32_e32 v88, v88, v19
	v_lshl_or_b32 v88, v88, 1, v21
	v_lshl_add_u64 v[90:91], v[26:27], 0, v[90:91]
	v_ashrrev_i32_e32 v89, 31, v88
	global_load_dword v100, v[90:91], off
	v_lshlrev_b64 v[90:91], 2, v[88:89]
	v_or_b32_e32 v90, v90, v20
	v_lshlrev_b64 v[102:103], 14, v[90:91]
	v_lshlrev_b64 v[90:91], 8, v[90:91]
	v_lshl_add_u64 v[90:91], v[12:13], 0, v[90:91]
	s_xor_b32 s0, s11, 0x7ffffff9
	global_load_dword v109, v[90:91], off
	v_add_u32_e32 v90, s0, v17
	s_add_i32 s0, s11, 6
	v_mov_b32_e32 v91, s0
	v_cndmask_b32_e64 v90, v90, v91, s[2:3]
	v_add_u32_e32 v90, v90, v19
	v_lshl_or_b32 v90, v90, 1, v21
	v_lshl_add_u64 v[102:103], v[26:27], 0, v[102:103]
	v_ashrrev_i32_e32 v91, 31, v90
	global_load_dword v108, v[102:103], off
	v_lshlrev_b64 v[102:103], 2, v[90:91]
	v_or_b32_e32 v102, v102, v20
	v_lshlrev_b64 v[104:105], 14, v[102:103]
	v_lshlrev_b64 v[102:103], 8, v[102:103]
	v_lshl_add_u64 v[102:103], v[12:13], 0, v[102:103]
	s_xor_b32 s0, s11, 0x7ffffff8
	global_load_dword v111, v[102:103], off
	v_add_u32_e32 v102, s0, v17
	s_add_i32 s0, s11, 7
	v_mov_b32_e32 v103, s0
	v_cndmask_b32_e64 v102, v102, v103, s[2:3]
	v_add_u32_e32 v102, v102, v19
	v_lshl_or_b32 v102, v102, 1, v21
	v_lshl_add_u64 v[104:105], v[26:27], 0, v[104:105]
	v_ashrrev_i32_e32 v103, 31, v102
	global_load_dword v110, v[104:105], off
	v_lshlrev_b64 v[104:105], 2, v[102:103]
	v_or_b32_e32 v104, v104, v20
	v_lshlrev_b64 v[106:107], 14, v[104:105]
	v_lshl_add_u64 v[106:107], v[26:27], 0, v[106:107]
	v_lshlrev_b64 v[104:105], 8, v[104:105]
	global_load_dword v106, v[106:107], off
	v_lshl_add_u64 v[104:105], v[12:13], 0, v[104:105]
	global_load_dword v104, v[104:105], off
	v_lshlrev_b64 v[78:79], 16, v[78:79]
	v_lshl_add_u64 v[78:79], v[28:29], 0, v[78:79]
	s_add_i32 s11, s11, 8
	v_add_u32_e32 v15, -8, v15
	v_mov_b32_e32 v119, s11
	v_cndmask_b32_e64 v119, v15, v119, s[2:3]
	v_add_u32_e32 v119, v119, v19
	v_lshl_or_b32 v126, v119, 1, v21
	v_ashrrev_i32_e32 v127, 31, v126
	v_lshlrev_b64 v[128:129], 2, v[126:127]
	v_or_b32_e32 v128, v128, v20
	v_lshlrev_b64 v[130:131], 14, v[128:129]
	v_lshlrev_b64 v[128:129], 8, v[128:129]
	v_lshl_add_u64 v[128:129], v[12:13], 0, v[128:129]
	s_xor_b32 s0, s11, 0x7ffffffe
	global_load_dword v141, v[128:129], off
	v_add_u32_e32 v128, s0, v17
	s_add_i32 s0, s11, 1
	v_mov_b32_e32 v129, s0
	v_cndmask_b32_e64 v128, v128, v129, s[2:3]
	v_add_u32_e32 v128, v128, v19
	v_lshl_or_b32 v128, v128, 1, v21
	v_lshl_add_u64 v[130:131], v[26:27], 0, v[130:131]
	v_ashrrev_i32_e32 v129, 31, v128
	global_load_dword v119, v[130:131], off
	v_lshlrev_b64 v[130:131], 2, v[128:129]
	v_or_b32_e32 v130, v130, v20
	v_lshlrev_b64 v[132:133], 14, v[130:131]
	v_lshlrev_b64 v[130:131], 8, v[130:131]
	v_lshl_add_u64 v[130:131], v[12:13], 0, v[130:131]
	s_xor_b32 s0, s11, 0x7ffffffd
	global_load_dword v143, v[130:131], off
	v_add_u32_e32 v130, s0, v17
	s_add_i32 s0, s11, 2
	v_mov_b32_e32 v131, s0
	v_cndmask_b32_e64 v130, v130, v131, s[2:3]
	v_add_u32_e32 v130, v130, v19
	v_lshl_or_b32 v130, v130, 1, v21
	v_lshl_add_u64 v[132:133], v[26:27], 0, v[132:133]
	v_ashrrev_i32_e32 v131, 31, v130
	global_load_dword v142, v[132:133], off
	v_lshlrev_b64 v[132:133], 2, v[130:131]
	v_or_b32_e32 v132, v132, v20
	v_lshlrev_b64 v[134:135], 14, v[132:133]
	v_lshlrev_b64 v[132:133], 8, v[132:133]
	v_lshl_add_u64 v[132:133], v[12:13], 0, v[132:133]
	s_xor_b32 s0, s11, 0x7ffffffc
	global_load_dword v145, v[132:133], off
	v_add_u32_e32 v132, s0, v17
	s_add_i32 s0, s11, 3
	v_mov_b32_e32 v133, s0
	v_cndmask_b32_e64 v132, v132, v133, s[2:3]
	v_add_u32_e32 v132, v132, v19
	v_lshl_or_b32 v132, v132, 1, v21
	v_lshl_add_u64 v[134:135], v[26:27], 0, v[134:135]
	v_ashrrev_i32_e32 v133, 31, v132
	global_load_dword v144, v[134:135], off
	v_lshlrev_b64 v[134:135], 2, v[132:133]
	v_or_b32_e32 v134, v134, v20
	v_lshlrev_b64 v[136:137], 14, v[134:135]
	v_lshlrev_b64 v[134:135], 8, v[134:135]
	v_lshl_add_u64 v[134:135], v[12:13], 0, v[134:135]
	s_xor_b32 s0, s11, 0x7ffffffb
	global_load_dword v147, v[134:135], off
	v_add_u32_e32 v134, s0, v17
	s_add_i32 s0, s11, 4
	v_mov_b32_e32 v135, s0
	v_cndmask_b32_e64 v134, v134, v135, s[2:3]
	v_add_u32_e32 v134, v134, v19
	v_lshl_or_b32 v134, v134, 1, v21
	v_lshl_add_u64 v[136:137], v[26:27], 0, v[136:137]
	v_ashrrev_i32_e32 v135, 31, v134
	global_load_dword v146, v[136:137], off
	v_lshlrev_b64 v[136:137], 2, v[134:135]
	v_or_b32_e32 v136, v136, v20
	v_lshlrev_b64 v[138:139], 14, v[136:137]
	v_lshlrev_b64 v[136:137], 8, v[136:137]
	v_lshl_add_u64 v[136:137], v[12:13], 0, v[136:137]
	s_xor_b32 s0, s11, 0x7ffffffa
	global_load_dword v149, v[136:137], off
	v_add_u32_e32 v136, s0, v17
	s_add_i32 s0, s11, 5
	v_mov_b32_e32 v137, s0
	v_cndmask_b32_e64 v136, v136, v137, s[2:3]
	v_add_u32_e32 v136, v136, v19
	v_lshl_or_b32 v136, v136, 1, v21
	v_lshl_add_u64 v[138:139], v[26:27], 0, v[138:139]
	v_ashrrev_i32_e32 v137, 31, v136
	global_load_dword v148, v[138:139], off
	v_lshlrev_b64 v[138:139], 2, v[136:137]
	v_or_b32_e32 v138, v138, v20
	v_lshlrev_b64 v[150:151], 14, v[138:139]
	v_lshlrev_b64 v[138:139], 8, v[138:139]
	v_lshl_add_u64 v[138:139], v[12:13], 0, v[138:139]
	s_xor_b32 s0, s11, 0x7ffffff9
	global_load_dword v157, v[138:139], off
	v_add_u32_e32 v138, s0, v17
	s_add_i32 s0, s11, 6
	v_mov_b32_e32 v139, s0
	v_cndmask_b32_e64 v138, v138, v139, s[2:3]
	v_add_u32_e32 v138, v138, v19
	v_lshl_or_b32 v138, v138, 1, v21
	v_lshl_add_u64 v[150:151], v[26:27], 0, v[150:151]
	v_ashrrev_i32_e32 v139, 31, v138
	global_load_dword v156, v[150:151], off
	v_lshlrev_b64 v[150:151], 2, v[138:139]
	v_or_b32_e32 v150, v150, v20
	v_lshlrev_b64 v[152:153], 14, v[150:151]
	v_lshlrev_b64 v[150:151], 8, v[150:151]
	v_lshl_add_u64 v[150:151], v[12:13], 0, v[150:151]
	s_xor_b32 s0, s11, 0x7ffffff8
	global_load_dword v159, v[150:151], off
	v_add_u32_e32 v150, s0, v17
	s_add_i32 s0, s11, 7
	v_mov_b32_e32 v151, s0
	v_cndmask_b32_e64 v150, v150, v151, s[2:3]
	v_add_u32_e32 v150, v150, v19
	v_lshl_or_b32 v150, v150, 1, v21
	v_lshl_add_u64 v[152:153], v[26:27], 0, v[152:153]
	v_ashrrev_i32_e32 v151, 31, v150
	global_load_dword v158, v[152:153], off
	v_lshlrev_b64 v[152:153], 2, v[150:151]
	v_or_b32_e32 v152, v152, v20
	v_lshlrev_b64 v[154:155], 14, v[152:153]
	v_lshl_add_u64 v[154:155], v[26:27], 0, v[154:155]
	v_lshlrev_b64 v[152:153], 8, v[152:153]
	global_load_dword v154, v[154:155], off
	v_lshl_add_u64 v[152:153], v[12:13], 0, v[152:153]
	global_load_dword v152, v[152:153], off
	v_lshlrev_b64 v[126:127], 16, v[126:127]
	v_lshl_add_u64 v[126:127], v[28:29], 0, v[126:127]
	s_add_i32 s11, s11, 8
	v_add_u32_e32 v15, -8, v15
	v_mov_b32_e32 v167, s11
	v_cndmask_b32_e64 v167, v15, v167, s[2:3]
	v_add_u32_e32 v167, v167, v19
	v_lshl_or_b32 v174, v167, 1, v21
	v_ashrrev_i32_e32 v175, 31, v174
	v_lshlrev_b64 v[176:177], 2, v[174:175]
	v_or_b32_e32 v176, v176, v20
	v_lshlrev_b64 v[178:179], 14, v[176:177]
	v_lshlrev_b64 v[176:177], 8, v[176:177]
	v_lshl_add_u64 v[176:177], v[12:13], 0, v[176:177]
	s_xor_b32 s0, s11, 0x7ffffffe
	global_load_dword v189, v[176:177], off
	v_add_u32_e32 v176, s0, v17
	s_add_i32 s0, s11, 1
	v_mov_b32_e32 v177, s0
	v_cndmask_b32_e64 v176, v176, v177, s[2:3]
	v_add_u32_e32 v176, v176, v19
	v_lshl_or_b32 v176, v176, 1, v21
	v_lshl_add_u64 v[178:179], v[26:27], 0, v[178:179]
	v_ashrrev_i32_e32 v177, 31, v176
	global_load_dword v167, v[178:179], off
	v_lshlrev_b64 v[178:179], 2, v[176:177]
	v_or_b32_e32 v178, v178, v20
	v_lshlrev_b64 v[180:181], 14, v[178:179]
	v_lshlrev_b64 v[178:179], 8, v[178:179]
	v_lshl_add_u64 v[178:179], v[12:13], 0, v[178:179]
	s_xor_b32 s0, s11, 0x7ffffffd
	global_load_dword v191, v[178:179], off
	v_add_u32_e32 v178, s0, v17
	s_add_i32 s0, s11, 2
	v_mov_b32_e32 v179, s0
	v_cndmask_b32_e64 v178, v178, v179, s[2:3]
	v_add_u32_e32 v178, v178, v19
	v_lshl_or_b32 v178, v178, 1, v21
	v_lshl_add_u64 v[180:181], v[26:27], 0, v[180:181]
	v_ashrrev_i32_e32 v179, 31, v178
	global_load_dword v190, v[180:181], off
	v_lshlrev_b64 v[180:181], 2, v[178:179]
	v_or_b32_e32 v180, v180, v20
	v_lshlrev_b64 v[182:183], 14, v[180:181]
	v_lshlrev_b64 v[180:181], 8, v[180:181]
	v_lshl_add_u64 v[180:181], v[12:13], 0, v[180:181]
	s_xor_b32 s0, s11, 0x7ffffffc
	global_load_dword v193, v[180:181], off
	v_add_u32_e32 v180, s0, v17
	s_add_i32 s0, s11, 3
	v_mov_b32_e32 v181, s0
	v_cndmask_b32_e64 v180, v180, v181, s[2:3]
	v_add_u32_e32 v180, v180, v19
	v_lshl_or_b32 v180, v180, 1, v21
	v_lshl_add_u64 v[182:183], v[26:27], 0, v[182:183]
	v_ashrrev_i32_e32 v181, 31, v180
	global_load_dword v192, v[182:183], off
	v_lshlrev_b64 v[182:183], 2, v[180:181]
	v_or_b32_e32 v182, v182, v20
	v_lshlrev_b64 v[184:185], 14, v[182:183]
	v_lshlrev_b64 v[182:183], 8, v[182:183]
	v_lshl_add_u64 v[182:183], v[12:13], 0, v[182:183]
	s_xor_b32 s0, s11, 0x7ffffffb
	global_load_dword v195, v[182:183], off
	v_add_u32_e32 v182, s0, v17
	s_add_i32 s0, s11, 4
	v_mov_b32_e32 v183, s0
	v_cndmask_b32_e64 v182, v182, v183, s[2:3]
	v_add_u32_e32 v182, v182, v19
	v_lshl_or_b32 v182, v182, 1, v21
	v_lshl_add_u64 v[184:185], v[26:27], 0, v[184:185]
	v_ashrrev_i32_e32 v183, 31, v182
	global_load_dword v194, v[184:185], off
	v_lshlrev_b64 v[184:185], 2, v[182:183]
	v_or_b32_e32 v184, v184, v20
	v_lshlrev_b64 v[186:187], 14, v[184:185]
	v_lshlrev_b64 v[184:185], 8, v[184:185]
	v_lshl_add_u64 v[184:185], v[12:13], 0, v[184:185]
	s_xor_b32 s0, s11, 0x7ffffffa
	global_load_dword v197, v[184:185], off
	v_add_u32_e32 v184, s0, v17
	s_add_i32 s0, s11, 5
	v_mov_b32_e32 v185, s0
	v_cndmask_b32_e64 v184, v184, v185, s[2:3]
	v_add_u32_e32 v184, v184, v19
	v_lshl_or_b32 v184, v184, 1, v21
	v_lshl_add_u64 v[186:187], v[26:27], 0, v[186:187]
	v_ashrrev_i32_e32 v185, 31, v184
	global_load_dword v196, v[186:187], off
	v_lshlrev_b64 v[186:187], 2, v[184:185]
	v_or_b32_e32 v186, v186, v20
	v_lshlrev_b64 v[198:199], 14, v[186:187]
	v_lshlrev_b64 v[186:187], 8, v[186:187]
	v_lshl_add_u64 v[186:187], v[12:13], 0, v[186:187]
	s_xor_b32 s0, s11, 0x7ffffff9
	global_load_dword v205, v[186:187], off
	v_add_u32_e32 v186, s0, v17
	s_add_i32 s0, s11, 6
	v_mov_b32_e32 v187, s0
	v_cndmask_b32_e64 v186, v186, v187, s[2:3]
	v_add_u32_e32 v186, v186, v19
	v_lshl_or_b32 v186, v186, 1, v21
	v_lshl_add_u64 v[198:199], v[26:27], 0, v[198:199]
	v_ashrrev_i32_e32 v187, 31, v186
	global_load_dword v204, v[198:199], off
	v_lshlrev_b64 v[198:199], 2, v[186:187]
	v_or_b32_e32 v198, v198, v20
	v_lshlrev_b64 v[200:201], 14, v[198:199]
	v_lshlrev_b64 v[198:199], 8, v[198:199]
	v_lshl_add_u64 v[198:199], v[12:13], 0, v[198:199]
	s_xor_b32 s0, s11, 0x7ffffff8
	global_load_dword v207, v[198:199], off
	v_add_u32_e32 v198, s0, v17
	s_add_i32 s0, s11, 7
	v_mov_b32_e32 v199, s0
	v_cndmask_b32_e64 v198, v198, v199, s[2:3]
	v_add_u32_e32 v198, v198, v19
	v_lshl_or_b32 v198, v198, 1, v21
	v_lshl_add_u64 v[200:201], v[26:27], 0, v[200:201]
	v_ashrrev_i32_e32 v199, 31, v198
	global_load_dword v206, v[200:201], off
	v_lshlrev_b64 v[200:201], 2, v[198:199]
	v_or_b32_e32 v200, v200, v20
	v_lshlrev_b64 v[202:203], 14, v[200:201]
	v_lshl_add_u64 v[202:203], v[26:27], 0, v[202:203]
	v_lshlrev_b64 v[200:201], 8, v[200:201]
	global_load_dword v202, v[202:203], off
	v_lshl_add_u64 v[200:201], v[12:13], 0, v[200:201]
	global_load_dword v200, v[200:201], off
	v_lshlrev_b64 v[174:175], 16, v[174:175]
	v_lshl_add_u64 v[174:175], v[28:29], 0, v[174:175]
	s_add_i32 s11, s11, 8
	v_add_u32_e32 v15, -8, v15
	s_waitcnt vmcnt(48)
	global_store_dword v[30:31], v44, off
	v_lshlrev_b64 v[30:31], 16, v[32:33]
	v_fmac_f32_e32 v23, v44, v45
	v_lshl_add_u64 v[30:31], v[28:29], 0, v[30:31]
	global_store_dword v[30:31], v23, off
	v_lshlrev_b64 v[30:31], 16, v[34:35]
	v_fmac_f32_e32 v46, v23, v47
	v_lshl_add_u64 v[30:31], v[28:29], 0, v[30:31]
	global_store_dword v[30:31], v46, off
	v_lshlrev_b64 v[30:31], 16, v[36:37]
	v_fmac_f32_e32 v48, v46, v49
	v_lshl_add_u64 v[30:31], v[28:29], 0, v[30:31]
	global_store_dword v[30:31], v48, off
	v_lshlrev_b64 v[30:31], 16, v[38:39]
	v_lshl_add_u64 v[30:31], v[28:29], 0, v[30:31]
	v_fmac_f32_e32 v50, v48, v51
	global_store_dword v[30:31], v50, off
	v_lshlrev_b64 v[30:31], 16, v[40:41]
	v_lshl_add_u64 v[30:31], v[28:29], 0, v[30:31]
	v_fmac_f32_e32 v52, v50, v53
	global_store_dword v[30:31], v52, off
	v_lshlrev_b64 v[30:31], 16, v[42:43]
	v_lshl_add_u64 v[30:31], v[28:29], 0, v[30:31]
	v_fmac_f32_e32 v60, v52, v61
	global_store_dword v[30:31], v60, off
	v_lshlrev_b64 v[30:31], 16, v[54:55]
	v_lshl_add_u64 v[30:31], v[28:29], 0, v[30:31]
	v_fmac_f32_e32 v62, v60, v63
	global_store_dword v[30:31], v62, off
	v_mov_b32_e32 v44, v58
	v_fmac_f32_e32 v44, v62, v56
	s_waitcnt vmcnt(40)
	global_store_dword v[78:79], v44, off
	v_lshlrev_b64 v[78:79], 16, v[80:81]
	v_fmac_f32_e32 v71, v44, v93
	v_lshl_add_u64 v[78:79], v[28:29], 0, v[78:79]
	global_store_dword v[78:79], v71, off
	v_lshlrev_b64 v[78:79], 16, v[82:83]
	v_fmac_f32_e32 v94, v71, v95
	v_lshl_add_u64 v[78:79], v[28:29], 0, v[78:79]
	global_store_dword v[78:79], v94, off
	v_lshlrev_b64 v[78:79], 16, v[84:85]
	v_fmac_f32_e32 v96, v94, v97
	v_lshl_add_u64 v[78:79], v[28:29], 0, v[78:79]
	global_store_dword v[78:79], v96, off
	v_lshlrev_b64 v[78:79], 16, v[86:87]
	v_lshl_add_u64 v[78:79], v[28:29], 0, v[78:79]
	v_fmac_f32_e32 v98, v96, v99
	global_store_dword v[78:79], v98, off
	v_lshlrev_b64 v[78:79], 16, v[88:89]
	v_lshl_add_u64 v[78:79], v[28:29], 0, v[78:79]
	v_fmac_f32_e32 v100, v98, v101
	global_store_dword v[78:79], v100, off
	v_lshlrev_b64 v[78:79], 16, v[90:91]
	v_lshl_add_u64 v[78:79], v[28:29], 0, v[78:79]
	v_fmac_f32_e32 v108, v100, v109
	global_store_dword v[78:79], v108, off
	v_lshlrev_b64 v[78:79], 16, v[102:103]
	v_lshl_add_u64 v[78:79], v[28:29], 0, v[78:79]
	v_fmac_f32_e32 v110, v108, v111
	global_store_dword v[78:79], v110, off
	v_mov_b32_e32 v44, v106
	v_fmac_f32_e32 v44, v110, v104
	s_waitcnt vmcnt(32)
	global_store_dword v[126:127], v44, off
	v_lshlrev_b64 v[126:127], 16, v[128:129]
	v_fmac_f32_e32 v119, v44, v141
	v_lshl_add_u64 v[126:127], v[28:29], 0, v[126:127]
	global_store_dword v[126:127], v119, off
	v_lshlrev_b64 v[126:127], 16, v[130:131]
	v_fmac_f32_e32 v142, v119, v143
	v_lshl_add_u64 v[126:127], v[28:29], 0, v[126:127]
	global_store_dword v[126:127], v142, off
	v_lshlrev_b64 v[126:127], 16, v[132:133]
	v_fmac_f32_e32 v144, v142, v145
	v_lshl_add_u64 v[126:127], v[28:29], 0, v[126:127]
	global_store_dword v[126:127], v144, off
	v_lshlrev_b64 v[126:127], 16, v[134:135]
	v_lshl_add_u64 v[126:127], v[28:29], 0, v[126:127]
	v_fmac_f32_e32 v146, v144, v147
	global_store_dword v[126:127], v146, off
	v_lshlrev_b64 v[126:127], 16, v[136:137]
	v_lshl_add_u64 v[126:127], v[28:29], 0, v[126:127]
	v_fmac_f32_e32 v148, v146, v149
	global_store_dword v[126:127], v148, off
	v_lshlrev_b64 v[126:127], 16, v[138:139]
	v_lshl_add_u64 v[126:127], v[28:29], 0, v[126:127]
	v_fmac_f32_e32 v156, v148, v157
	global_store_dword v[126:127], v156, off
	v_lshlrev_b64 v[126:127], 16, v[150:151]
	v_lshl_add_u64 v[126:127], v[28:29], 0, v[126:127]
	v_fmac_f32_e32 v158, v156, v159
	global_store_dword v[126:127], v158, off
	v_mov_b32_e32 v44, v154
	v_fmac_f32_e32 v44, v158, v152
	s_waitcnt vmcnt(24)
	global_store_dword v[174:175], v44, off
	v_lshlrev_b64 v[174:175], 16, v[176:177]
	v_fmac_f32_e32 v167, v44, v189
	v_lshl_add_u64 v[174:175], v[28:29], 0, v[174:175]
	global_store_dword v[174:175], v167, off
	v_lshlrev_b64 v[174:175], 16, v[178:179]
	v_fmac_f32_e32 v190, v167, v191
	v_lshl_add_u64 v[174:175], v[28:29], 0, v[174:175]
	global_store_dword v[174:175], v190, off
	v_lshlrev_b64 v[174:175], 16, v[180:181]
	v_fmac_f32_e32 v192, v190, v193
	v_lshl_add_u64 v[174:175], v[28:29], 0, v[174:175]
	global_store_dword v[174:175], v192, off
	v_lshlrev_b64 v[174:175], 16, v[182:183]
	v_lshl_add_u64 v[174:175], v[28:29], 0, v[174:175]
	v_fmac_f32_e32 v194, v192, v195
	global_store_dword v[174:175], v194, off
	v_lshlrev_b64 v[174:175], 16, v[184:185]
	v_lshl_add_u64 v[174:175], v[28:29], 0, v[174:175]
	v_fmac_f32_e32 v196, v194, v197
	global_store_dword v[174:175], v196, off
	v_lshlrev_b64 v[174:175], 16, v[186:187]
	v_lshl_add_u64 v[174:175], v[28:29], 0, v[174:175]
	v_fmac_f32_e32 v204, v196, v205
	global_store_dword v[174:175], v204, off
	v_lshlrev_b64 v[174:175], 16, v[198:199]
	v_lshl_add_u64 v[174:175], v[28:29], 0, v[174:175]
	v_fmac_f32_e32 v206, v204, v207
	global_store_dword v[174:175], v206, off
	v_mov_b32_e32 v44, v202
	v_fmac_f32_e32 v44, v206, v200
	s_branch .Lhgscan_done

.Lhgscan_done:
	s_or_b64 exec, exec, s[8:9]
	s_and_saveexec_b64 s[0:1], vcc
	s_cbranch_execz .LBB0_1065
	v_ashrrev_i32_e32 v17, 31, v16
	v_lshlrev_b64 v[16:17], 2, v[16:17]
	v_or_b32_e32 v15, v16, v21
	v_or_b32_e32 v16, s10, v15
	v_lshlrev_b64 v[16:17], 16, v[16:17]
	v_lshl_add_u64 v[16:17], v[2:3], 0, v[16:17]
	v_lshl_add_u64 v[16:17], v[24:25], 2, v[16:17]
	v_mov_b32_e32 v23, v229
	v_lshl_add_u64 v[16:17], v[16:17], 0, v[22:23]
	v_mov_b32_e32 v19, v229
	v_lshl_add_u64 v[16:17], v[16:17], 0, v[18:19]
	v_add_co_u32_e32 v16, vcc, 0x2080000, v16
	s_nop 1
	v_addc_co_u32_e32 v17, vcc, 0, v17, vcc
	flat_store_dword v[16:17], v44
	s_branch .LBB0_1065

.LBB0_1079:
	s_or_b64 exec, exec, s[0:1]
	v_and_b32_e32 v15, 0xfffff800, v5
	v_add_u32_e32 v15, 0xffff9000, v15
	v_lshlrev_b32_e32 v20, 8, v14
	v_cmp_gt_i32_e32 vcc, 16, v14
	s_mov_b32 s12, 0
	v_cmp_eq_u32_e64 s[2:3], 0, v54
	v_cndmask_b32_e32 v20, v15, v20, vcc
	v_cndmask_b32_e64 v15, 64, 8, vcc
	v_ashrrev_i32_e32 v55, 5, v20
	s_waitcnt vmcnt(0) lgkmcnt(0)
	v_mov_b32_e32 v20, v18
	v_mov_b32_e32 v21, v18
	v_or_b32_e32 v56, v22, v53
	v_pk_mov_b32 v[22:23], v[18:19], v[18:19] op_sel:[1,0]
	v_mov_b32_e32 v24, v19
	v_mov_b32_e32 v25, v19
	v_add_u32_e32 v57, -1, v15
	s_mov_b64 s[8:9], 0
	v_cmp_ne_u32_e64 s[0:1], 64, v15
	s_cmp_lg_u64 s[0:1], 0
	s_cbranch_scc1 .LBB0_1080
	v_mov_b32_e32 v197, 0
	v_mov_b32_e32 v198, 0x4000
	v_mov_b32_e32 v199, 0
	v_mov_b32_e32 v204, 0xffffc000
	v_mov_b32_e32 v205, -1
	v_cndmask_b32_e64 v196, v57, v197, s[2:3]
	v_cndmask_b32_e64 v198, v204, v198, s[2:3]
	v_cndmask_b32_e64 v199, v205, v199, s[2:3]
	v_add_u32_e32 v196, v196, v55
	v_lshl_or_b32 v196, v196, 5, v56
	v_ashrrev_i32_e32 v197, 31, v196
	v_lshlrev_b64 v[202:203], 9, v[196:197]
	v_lshl_add_u64 v[196:197], v[10:11], 0, v[202:203]
	v_lshl_add_u64 v[200:201], v[12:13], 0, v[202:203]
	global_load_dwordx2 v[68:69], v[196:197], off
	v_lshl_add_u64 v[196:197], v[196:197], 0, v[198:199]
	global_load_dwordx2 v[70:71], v[196:197], off
	v_lshl_add_u64 v[196:197], v[196:197], 0, v[198:199]
	global_load_dwordx2 v[72:73], v[196:197], off
	v_lshl_add_u64 v[196:197], v[196:197], 0, v[198:199]
	global_load_dwordx2 v[74:75], v[196:197], off
	v_lshl_add_u64 v[196:197], v[196:197], 0, v[198:199]
	global_load_dwordx2 v[76:77], v[196:197], off
	v_lshl_add_u64 v[196:197], v[196:197], 0, v[198:199]
	global_load_dwordx2 v[78:79], v[196:197], off
	v_lshl_add_u64 v[196:197], v[196:197], 0, v[198:199]
	global_load_dwordx2 v[80:81], v[196:197], off
	v_lshl_add_u64 v[196:197], v[196:197], 0, v[198:199]
	global_load_dwordx2 v[82:83], v[196:197], off
	v_lshl_add_u64 v[196:197], v[196:197], 0, v[198:199]
	global_load_dwordx2 v[84:85], v[196:197], off
	v_lshl_add_u64 v[196:197], v[196:197], 0, v[198:199]
	global_load_dwordx2 v[86:87], v[196:197], off
	v_lshl_add_u64 v[196:197], v[196:197], 0, v[198:199]
	global_load_dwordx2 v[88:89], v[196:197], off
	v_lshl_add_u64 v[196:197], v[196:197], 0, v[198:199]
	global_load_dwordx2 v[90:91], v[196:197], off
	v_lshl_add_u64 v[196:197], v[196:197], 0, v[198:199]
	global_load_dwordx2 v[92:93], v[196:197], off
	v_lshl_add_u64 v[196:197], v[196:197], 0, v[198:199]
	global_load_dwordx2 v[94:95], v[196:197], off
	v_lshl_add_u64 v[196:197], v[196:197], 0, v[198:199]
	global_load_dwordx2 v[96:97], v[196:197], off
	v_lshl_add_u64 v[196:197], v[196:197], 0, v[198:199]
	global_load_dwordx2 v[98:99], v[196:197], off
	v_lshl_add_u64 v[196:197], v[196:197], 0, v[198:199]
	global_load_dwordx2 v[100:101], v[196:197], off
	v_lshl_add_u64 v[196:197], v[196:197], 0, v[198:199]
	global_load_dwordx2 v[102:103], v[196:197], off
	v_lshl_add_u64 v[196:197], v[196:197], 0, v[198:199]
	global_load_dwordx2 v[104:105], v[196:197], off
	v_lshl_add_u64 v[196:197], v[196:197], 0, v[198:199]
	global_load_dwordx2 v[106:107], v[196:197], off
	v_lshl_add_u64 v[196:197], v[196:197], 0, v[198:199]
	global_load_dwordx2 v[108:109], v[196:197], off
	v_lshl_add_u64 v[196:197], v[196:197], 0, v[198:199]
	global_load_dwordx2 v[110:111], v[196:197], off
	v_lshl_add_u64 v[196:197], v[196:197], 0, v[198:199]
	global_load_dwordx2 v[112:113], v[196:197], off
	v_lshl_add_u64 v[196:197], v[196:197], 0, v[198:199]
	global_load_dwordx2 v[114:115], v[196:197], off
	v_lshl_add_u64 v[196:197], v[196:197], 0, v[198:199]
	global_load_dwordx2 v[116:117], v[196:197], off
	v_lshl_add_u64 v[196:197], v[196:197], 0, v[198:199]
	global_load_dwordx2 v[118:119], v[196:197], off
	v_lshl_add_u64 v[196:197], v[196:197], 0, v[198:199]
	global_load_dwordx2 v[120:121], v[196:197], off
	v_lshl_add_u64 v[196:197], v[196:197], 0, v[198:199]
	global_load_dwordx2 v[122:123], v[196:197], off
	v_lshl_add_u64 v[196:197], v[196:197], 0, v[198:199]
	global_load_dwordx2 v[124:125], v[196:197], off
	v_lshl_add_u64 v[196:197], v[196:197], 0, v[198:199]
	global_load_dwordx2 v[126:127], v[196:197], off
	v_lshl_add_u64 v[196:197], v[196:197], 0, v[198:199]
	global_load_dwordx2 v[128:129], v[196:197], off
	v_lshl_add_u64 v[196:197], v[196:197], 0, v[198:199]
	global_load_dwordx2 v[130:131], v[196:197], off
	v_lshl_add_u64 v[196:197], v[196:197], 0, v[198:199]
	global_load_dwordx2 v[132:133], v[196:197], off
	v_lshl_add_u64 v[196:197], v[196:197], 0, v[198:199]
	global_load_dwordx2 v[134:135], v[196:197], off
	v_lshl_add_u64 v[196:197], v[196:197], 0, v[198:199]
	global_load_dwordx2 v[136:137], v[196:197], off
	v_lshl_add_u64 v[196:197], v[196:197], 0, v[198:199]
	global_load_dwordx2 v[138:139], v[196:197], off
	v_lshl_add_u64 v[196:197], v[196:197], 0, v[198:199]
	global_load_dwordx2 v[140:141], v[196:197], off
	v_lshl_add_u64 v[196:197], v[196:197], 0, v[198:199]
	global_load_dwordx2 v[142:143], v[196:197], off
	v_lshl_add_u64 v[196:197], v[196:197], 0, v[198:199]
	global_load_dwordx2 v[144:145], v[196:197], off
	v_lshl_add_u64 v[196:197], v[196:197], 0, v[198:199]
	global_load_dwordx2 v[146:147], v[196:197], off
	v_lshl_add_u64 v[196:197], v[196:197], 0, v[198:199]
	global_load_dwordx2 v[148:149], v[196:197], off
	v_lshl_add_u64 v[196:197], v[196:197], 0, v[198:199]
	global_load_dwordx2 v[150:151], v[196:197], off
	v_lshl_add_u64 v[196:197], v[196:197], 0, v[198:199]
	global_load_dwordx2 v[152:153], v[196:197], off
	v_lshl_add_u64 v[196:197], v[196:197], 0, v[198:199]
	global_load_dwordx2 v[154:155], v[196:197], off
	v_lshl_add_u64 v[196:197], v[196:197], 0, v[198:199]
	global_load_dwordx2 v[156:157], v[196:197], off
	v_lshl_add_u64 v[196:197], v[196:197], 0, v[198:199]
	global_load_dwordx2 v[158:159], v[196:197], off
	v_lshl_add_u64 v[196:197], v[196:197], 0, v[198:199]
	global_load_dwordx2 v[160:161], v[196:197], off
	v_lshl_add_u64 v[196:197], v[196:197], 0, v[198:199]
	global_load_dwordx2 v[162:163], v[196:197], off
	v_lshl_add_u64 v[196:197], v[196:197], 0, v[198:199]
	global_load_dwordx2 v[164:165], v[196:197], off
	v_lshl_add_u64 v[196:197], v[196:197], 0, v[198:199]
	global_load_dwordx2 v[166:167], v[196:197], off
	v_lshl_add_u64 v[196:197], v[196:197], 0, v[198:199]
	global_load_dwordx2 v[168:169], v[196:197], off
	v_lshl_add_u64 v[196:197], v[196:197], 0, v[198:199]
	global_load_dwordx2 v[170:171], v[196:197], off
	v_lshl_add_u64 v[196:197], v[196:197], 0, v[198:199]
	global_load_dwordx2 v[172:173], v[196:197], off
	v_lshl_add_u64 v[196:197], v[196:197], 0, v[198:199]
	global_load_dwordx2 v[174:175], v[196:197], off
	v_lshl_add_u64 v[196:197], v[196:197], 0, v[198:199]
	global_load_dwordx2 v[176:177], v[196:197], off
	v_lshl_add_u64 v[196:197], v[196:197], 0, v[198:199]
	global_load_dwordx2 v[178:179], v[196:197], off
	v_lshl_add_u64 v[196:197], v[196:197], 0, v[198:199]
	global_load_dwordx2 v[180:181], v[196:197], off
	v_lshl_add_u64 v[196:197], v[196:197], 0, v[198:199]
	global_load_dwordx2 v[182:183], v[196:197], off
	v_lshl_add_u64 v[196:197], v[196:197], 0, v[198:199]
	global_load_dwordx2 v[184:185], v[196:197], off
	v_lshl_add_u64 v[196:197], v[196:197], 0, v[198:199]
	global_load_dwordx2 v[186:187], v[196:197], off
	v_lshl_add_u64 v[196:197], v[196:197], 0, v[198:199]
	global_load_dwordx2 v[188:189], v[196:197], off
	v_lshl_add_u64 v[196:197], v[196:197], 0, v[198:199]
	global_load_dwordx2 v[190:191], v[196:197], off
	v_lshl_add_u64 v[196:197], v[196:197], 0, v[198:199]
	global_load_dwordx2 v[192:193], v[196:197], off
	v_lshl_add_u64 v[196:197], v[196:197], 0, v[198:199]
	global_load_dwordx2 v[194:195], v[196:197], off
	v_lshl_add_u64 v[196:197], v[196:197], 0, v[198:199]
	global_store_dwordx2 v[200:201], v[16:17], off
	v_lshl_add_u64 v[200:201], v[200:201], 0, v[198:199]
	v_pk_mul_f32 v[64:65], v[22:23], v[16:17] op_sel:[0,1]
	s_nop 0
	v_pk_fma_f32 v[66:67], v[18:19], v[16:17], v[64:65] neg_lo:[0,0,1] neg_hi:[0,0,1]
	v_pk_fma_f32 v[64:65], v[18:19], v[16:17], v[64:65] op_sel_hi:[1,0,1]
	s_nop 0
	v_mov_b32_e32 v67, v65
	v_pk_add_f32 v[68:69], v[68:69], v[66:67]
	s_nop 0
	v_pk_mul_f32 v[64:65], v[22:23], v[68:69] op_sel:[0,1]
	s_nop 0
	v_pk_fma_f32 v[66:67], v[18:19], v[68:69], v[64:65] neg_lo:[0,0,1] neg_hi:[0,0,1]
	v_pk_fma_f32 v[64:65], v[18:19], v[68:69], v[64:65] op_sel_hi:[1,0,1]
	s_nop 0
	v_mov_b32_e32 v67, v65
	s_waitcnt vmcnt(63)
	v_pk_add_f32 v[70:71], v[70:71], v[66:67]
	s_nop 0
	v_pk_mul_f32 v[64:65], v[22:23], v[70:71] op_sel:[0,1]
	s_nop 0
	v_pk_fma_f32 v[66:67], v[18:19], v[70:71], v[64:65] neg_lo:[0,0,1] neg_hi:[0,0,1]
	v_pk_fma_f32 v[64:65], v[18:19], v[70:71], v[64:65] op_sel_hi:[1,0,1]
	s_nop 0
	v_mov_b32_e32 v67, v65
	s_waitcnt vmcnt(62)
	v_pk_add_f32 v[72:73], v[72:73], v[66:67]
	s_nop 0
	v_pk_mul_f32 v[64:65], v[22:23], v[72:73] op_sel:[0,1]
	s_nop 0
	v_pk_fma_f32 v[66:67], v[18:19], v[72:73], v[64:65] neg_lo:[0,0,1] neg_hi:[0,0,1]
	v_pk_fma_f32 v[64:65], v[18:19], v[72:73], v[64:65] op_sel_hi:[1,0,1]
	s_nop 0
	v_mov_b32_e32 v67, v65
	s_waitcnt vmcnt(61)
	v_pk_add_f32 v[74:75], v[74:75], v[66:67]
	s_nop 0
	v_pk_mul_f32 v[64:65], v[22:23], v[74:75] op_sel:[0,1]
	s_nop 0
	v_pk_fma_f32 v[66:67], v[18:19], v[74:75], v[64:65] neg_lo:[0,0,1] neg_hi:[0,0,1]
	v_pk_fma_f32 v[64:65], v[18:19], v[74:75], v[64:65] op_sel_hi:[1,0,1]
	s_nop 0
	v_mov_b32_e32 v67, v65
	s_waitcnt vmcnt(60)
	v_pk_add_f32 v[76:77], v[76:77], v[66:67]
	s_nop 0
	v_pk_mul_f32 v[64:65], v[22:23], v[76:77] op_sel:[0,1]
	s_nop 0
	v_pk_fma_f32 v[66:67], v[18:19], v[76:77], v[64:65] neg_lo:[0,0,1] neg_hi:[0,0,1]
	v_pk_fma_f32 v[64:65], v[18:19], v[76:77], v[64:65] op_sel_hi:[1,0,1]
	s_nop 0
	v_mov_b32_e32 v67, v65
	s_waitcnt vmcnt(59)
	v_pk_add_f32 v[78:79], v[78:79], v[66:67]
	s_nop 0
	v_pk_mul_f32 v[64:65], v[22:23], v[78:79] op_sel:[0,1]
	s_nop 0
	v_pk_fma_f32 v[66:67], v[18:19], v[78:79], v[64:65] neg_lo:[0,0,1] neg_hi:[0,0,1]
	v_pk_fma_f32 v[64:65], v[18:19], v[78:79], v[64:65] op_sel_hi:[1,0,1]
	s_nop 0
	v_mov_b32_e32 v67, v65
	s_waitcnt vmcnt(58)
	v_pk_add_f32 v[80:81], v[80:81], v[66:67]
	s_nop 0
	v_pk_mul_f32 v[64:65], v[24:25], v[80:81] op_sel:[0,1] op_sel_hi:[1,0]
	s_nop 0
	v_pk_fma_f32 v[66:67], v[20:21], v[80:81], v[64:65] neg_lo:[0,0,1] neg_hi:[0,0,1]
	v_pk_fma_f32 v[64:65], v[20:21], v[80:81], v[64:65]
	s_nop 0
	v_mov_b32_e32 v67, v65
	s_waitcnt vmcnt(57)
	v_pk_add_f32 v[82:83], v[82:83], v[66:67]
	s_nop 0
	v_pk_mul_f32 v[64:65], v[22:23], v[82:83] op_sel:[0,1]
	s_nop 0
	v_pk_fma_f32 v[66:67], v[18:19], v[82:83], v[64:65] neg_lo:[0,0,1] neg_hi:[0,0,1]
	v_pk_fma_f32 v[64:65], v[18:19], v[82:83], v[64:65] op_sel_hi:[1,0,1]
	s_nop 0
	v_mov_b32_e32 v67, v65
	s_waitcnt vmcnt(56)
	v_pk_add_f32 v[84:85], v[84:85], v[66:67]
	s_nop 0
	v_pk_mul_f32 v[64:65], v[22:23], v[84:85] op_sel:[0,1]
	s_nop 0
	v_pk_fma_f32 v[66:67], v[18:19], v[84:85], v[64:65] neg_lo:[0,0,1] neg_hi:[0,0,1]
	v_pk_fma_f32 v[64:65], v[18:19], v[84:85], v[64:65] op_sel_hi:[1,0,1]
	s_nop 0
	v_mov_b32_e32 v67, v65
	s_waitcnt vmcnt(55)
	v_pk_add_f32 v[86:87], v[86:87], v[66:67]
	s_nop 0
	v_pk_mul_f32 v[64:65], v[22:23], v[86:87] op_sel:[0,1]
	s_nop 0
	v_pk_fma_f32 v[66:67], v[18:19], v[86:87], v[64:65] neg_lo:[0,0,1] neg_hi:[0,0,1]
	v_pk_fma_f32 v[64:65], v[18:19], v[86:87], v[64:65] op_sel_hi:[1,0,1]
	s_nop 0
	v_mov_b32_e32 v67, v65
	s_waitcnt vmcnt(54)
	v_pk_add_f32 v[88:89], v[88:89], v[66:67]
	s_nop 0
	v_pk_mul_f32 v[64:65], v[22:23], v[88:89] op_sel:[0,1]
	s_nop 0
	v_pk_fma_f32 v[66:67], v[18:19], v[88:89], v[64:65] neg_lo:[0,0,1] neg_hi:[0,0,1]
	v_pk_fma_f32 v[64:65], v[18:19], v[88:89], v[64:65] op_sel_hi:[1,0,1]
	s_nop 0
	v_mov_b32_e32 v67, v65
	s_waitcnt vmcnt(53)
	v_pk_add_f32 v[90:91], v[90:91], v[66:67]
	s_nop 0
	v_pk_mul_f32 v[64:65], v[22:23], v[90:91] op_sel:[0,1]
	s_nop 0
	v_pk_fma_f32 v[66:67], v[18:19], v[90:91], v[64:65] neg_lo:[0,0,1] neg_hi:[0,0,1]
	v_pk_fma_f32 v[64:65], v[18:19], v[90:91], v[64:65] op_sel_hi:[1,0,1]
	s_nop 0
	v_mov_b32_e32 v67, v65
	s_waitcnt vmcnt(52)
	v_pk_add_f32 v[92:93], v[92:93], v[66:67]
	s_nop 0
	v_pk_mul_f32 v[64:65], v[22:23], v[92:93] op_sel:[0,1]
	s_nop 0
	v_pk_fma_f32 v[66:67], v[18:19], v[92:93], v[64:65] neg_lo:[0,0,1] neg_hi:[0,0,1]
	v_pk_fma_f32 v[64:65], v[18:19], v[92:93], v[64:65] op_sel_hi:[1,0,1]
	s_nop 0
	v_mov_b32_e32 v67, v65
	s_waitcnt vmcnt(51)
	v_pk_add_f32 v[94:95], v[94:95], v[66:67]
	s_nop 0
	v_pk_mul_f32 v[64:65], v[22:23], v[94:95] op_sel:[0,1]
	s_nop 0
	v_pk_fma_f32 v[66:67], v[18:19], v[94:95], v[64:65] neg_lo:[0,0,1] neg_hi:[0,0,1]
	v_pk_fma_f32 v[64:65], v[18:19], v[94:95], v[64:65] op_sel_hi:[1,0,1]
	s_nop 0
	v_mov_b32_e32 v67, v65
	s_waitcnt vmcnt(50)
	v_pk_add_f32 v[96:97], v[96:97], v[66:67]
	s_nop 0
	v_pk_mul_f32 v[64:65], v[24:25], v[96:97] op_sel:[0,1] op_sel_hi:[1,0]
	s_nop 0
	v_pk_fma_f32 v[66:67], v[20:21], v[96:97], v[64:65] neg_lo:[0,0,1] neg_hi:[0,0,1]
	v_pk_fma_f32 v[64:65], v[20:21], v[96:97], v[64:65]
	s_nop 0
	v_mov_b32_e32 v67, v65
	s_waitcnt vmcnt(49)
	v_pk_add_f32 v[98:99], v[98:99], v[66:67]
	s_nop 0
	v_pk_mul_f32 v[64:65], v[22:23], v[98:99] op_sel:[0,1]
	s_nop 0
	v_pk_fma_f32 v[66:67], v[18:19], v[98:99], v[64:65] neg_lo:[0,0,1] neg_hi:[0,0,1]
	v_pk_fma_f32 v[64:65], v[18:19], v[98:99], v[64:65] op_sel_hi:[1,0,1]
	s_nop 0
	v_mov_b32_e32 v67, v65
	s_waitcnt vmcnt(48)
	v_pk_add_f32 v[100:101], v[100:101], v[66:67]
	s_nop 0
	v_pk_mul_f32 v[64:65], v[22:23], v[100:101] op_sel:[0,1]
	s_nop 0
	v_pk_fma_f32 v[66:67], v[18:19], v[100:101], v[64:65] neg_lo:[0,0,1] neg_hi:[0,0,1]
	v_pk_fma_f32 v[64:65], v[18:19], v[100:101], v[64:65] op_sel_hi:[1,0,1]
	s_nop 0
	v_mov_b32_e32 v67, v65
	s_waitcnt vmcnt(47)
	v_pk_add_f32 v[102:103], v[102:103], v[66:67]
	s_nop 0
	v_pk_mul_f32 v[64:65], v[22:23], v[102:103] op_sel:[0,1]
	s_nop 0
	v_pk_fma_f32 v[66:67], v[18:19], v[102:103], v[64:65] neg_lo:[0,0,1] neg_hi:[0,0,1]
	v_pk_fma_f32 v[64:65], v[18:19], v[102:103], v[64:65] op_sel_hi:[1,0,1]
	s_nop 0
	v_mov_b32_e32 v67, v65
	s_waitcnt vmcnt(46)
	v_pk_add_f32 v[104:105], v[104:105], v[66:67]
	s_nop 0
	v_pk_mul_f32 v[64:65], v[22:23], v[104:105] op_sel:[0,1]
	s_nop 0
	v_pk_fma_f32 v[66:67], v[18:19], v[104:105], v[64:65] neg_lo:[0,0,1] neg_hi:[0,0,1]
	v_pk_fma_f32 v[64:65], v[18:19], v[104:105], v[64:65] op_sel_hi:[1,0,1]
	s_nop 0
	v_mov_b32_e32 v67, v65
	s_waitcnt vmcnt(45)
	v_pk_add_f32 v[106:107], v[106:107], v[66:67]
	s_nop 0
	v_pk_mul_f32 v[64:65], v[22:23], v[106:107] op_sel:[0,1]
	s_nop 0
	v_pk_fma_f32 v[66:67], v[18:19], v[106:107], v[64:65] neg_lo:[0,0,1] neg_hi:[0,0,1]
	v_pk_fma_f32 v[64:65], v[18:19], v[106:107], v[64:65] op_sel_hi:[1,0,1]
	s_nop 0
	v_mov_b32_e32 v67, v65
	s_waitcnt vmcnt(44)
	v_pk_add_f32 v[108:109], v[108:109], v[66:67]
	s_nop 0
	v_pk_mul_f32 v[64:65], v[22:23], v[108:109] op_sel:[0,1]
	s_nop 0
	v_pk_fma_f32 v[66:67], v[18:19], v[108:109], v[64:65] neg_lo:[0,0,1] neg_hi:[0,0,1]
	v_pk_fma_f32 v[64:65], v[18:19], v[108:109], v[64:65] op_sel_hi:[1,0,1]
	s_nop 0
	v_mov_b32_e32 v67, v65
	s_waitcnt vmcnt(43)
	v_pk_add_f32 v[110:111], v[110:111], v[66:67]
	s_nop 0
	v_pk_mul_f32 v[64:65], v[22:23], v[110:111] op_sel:[0,1]
	s_nop 0
	v_pk_fma_f32 v[66:67], v[18:19], v[110:111], v[64:65] neg_lo:[0,0,1] neg_hi:[0,0,1]
	v_pk_fma_f32 v[64:65], v[18:19], v[110:111], v[64:65] op_sel_hi:[1,0,1]
	s_nop 0
	v_mov_b32_e32 v67, v65
	s_waitcnt vmcnt(42)
	v_pk_add_f32 v[112:113], v[112:113], v[66:67]
	s_nop 0
	v_pk_mul_f32 v[64:65], v[24:25], v[112:113] op_sel:[0,1] op_sel_hi:[1,0]
	s_nop 0
	v_pk_fma_f32 v[66:67], v[20:21], v[112:113], v[64:65] neg_lo:[0,0,1] neg_hi:[0,0,1]
	v_pk_fma_f32 v[64:65], v[20:21], v[112:113], v[64:65]
	s_nop 0
	v_mov_b32_e32 v67, v65
	s_waitcnt vmcnt(41)
	v_pk_add_f32 v[114:115], v[114:115], v[66:67]
	s_nop 0
	v_pk_mul_f32 v[64:65], v[22:23], v[114:115] op_sel:[0,1]
	s_nop 0
	v_pk_fma_f32 v[66:67], v[18:19], v[114:115], v[64:65] neg_lo:[0,0,1] neg_hi:[0,0,1]
	v_pk_fma_f32 v[64:65], v[18:19], v[114:115], v[64:65] op_sel_hi:[1,0,1]
	s_nop 0
	v_mov_b32_e32 v67, v65
	s_waitcnt vmcnt(40)
	v_pk_add_f32 v[116:117], v[116:117], v[66:67]
	s_nop 0
	v_pk_mul_f32 v[64:65], v[22:23], v[116:117] op_sel:[0,1]
	s_nop 0
	v_pk_fma_f32 v[66:67], v[18:19], v[116:117], v[64:65] neg_lo:[0,0,1] neg_hi:[0,0,1]
	v_pk_fma_f32 v[64:65], v[18:19], v[116:117], v[64:65] op_sel_hi:[1,0,1]
	s_nop 0
	v_mov_b32_e32 v67, v65
	s_waitcnt vmcnt(39)
	v_pk_add_f32 v[118:119], v[118:119], v[66:67]
	s_nop 0
	v_pk_mul_f32 v[64:65], v[22:23], v[118:119] op_sel:[0,1]
	s_nop 0
	v_pk_fma_f32 v[66:67], v[18:19], v[118:119], v[64:65] neg_lo:[0,0,1] neg_hi:[0,0,1]
	v_pk_fma_f32 v[64:65], v[18:19], v[118:119], v[64:65] op_sel_hi:[1,0,1]
	s_nop 0
	v_mov_b32_e32 v67, v65
	s_waitcnt vmcnt(38)
	v_pk_add_f32 v[120:121], v[120:121], v[66:67]
	s_nop 0
	v_pk_mul_f32 v[64:65], v[22:23], v[120:121] op_sel:[0,1]
	s_nop 0
	v_pk_fma_f32 v[66:67], v[18:19], v[120:121], v[64:65] neg_lo:[0,0,1] neg_hi:[0,0,1]
	v_pk_fma_f32 v[64:65], v[18:19], v[120:121], v[64:65] op_sel_hi:[1,0,1]
	s_nop 0
	v_mov_b32_e32 v67, v65
	s_waitcnt vmcnt(37)
	v_pk_add_f32 v[122:123], v[122:123], v[66:67]
	s_nop 0
	v_pk_mul_f32 v[64:65], v[22:23], v[122:123] op_sel:[0,1]
	s_nop 0
	v_pk_fma_f32 v[66:67], v[18:19], v[122:123], v[64:65] neg_lo:[0,0,1] neg_hi:[0,0,1]
	v_pk_fma_f32 v[64:65], v[18:19], v[122:123], v[64:65] op_sel_hi:[1,0,1]
	s_nop 0
	v_mov_b32_e32 v67, v65
	s_waitcnt vmcnt(36)
	v_pk_add_f32 v[124:125], v[124:125], v[66:67]
	s_nop 0
	v_pk_mul_f32 v[64:65], v[22:23], v[124:125] op_sel:[0,1]
	s_nop 0
	v_pk_fma_f32 v[66:67], v[18:19], v[124:125], v[64:65] neg_lo:[0,0,1] neg_hi:[0,0,1]
	v_pk_fma_f32 v[64:65], v[18:19], v[124:125], v[64:65] op_sel_hi:[1,0,1]
	s_nop 0
	v_mov_b32_e32 v67, v65
	s_waitcnt vmcnt(35)
	v_pk_add_f32 v[126:127], v[126:127], v[66:67]
	s_nop 0
	v_pk_mul_f32 v[64:65], v[22:23], v[126:127] op_sel:[0,1]
	s_nop 0
	v_pk_fma_f32 v[66:67], v[18:19], v[126:127], v[64:65] neg_lo:[0,0,1] neg_hi:[0,0,1]
	v_pk_fma_f32 v[64:65], v[18:19], v[126:127], v[64:65] op_sel_hi:[1,0,1]
	s_nop 0
	v_mov_b32_e32 v67, v65
	s_waitcnt vmcnt(34)
	v_pk_add_f32 v[128:129], v[128:129], v[66:67]
	s_nop 0
	v_pk_mul_f32 v[64:65], v[24:25], v[128:129] op_sel:[0,1] op_sel_hi:[1,0]
	s_nop 0
	v_pk_fma_f32 v[66:67], v[20:21], v[128:129], v[64:65] neg_lo:[0,0,1] neg_hi:[0,0,1]
	v_pk_fma_f32 v[64:65], v[20:21], v[128:129], v[64:65]
	s_nop 0
	v_mov_b32_e32 v67, v65
	s_waitcnt vmcnt(33)
	v_pk_add_f32 v[130:131], v[130:131], v[66:67]
	s_nop 0
	v_pk_mul_f32 v[64:65], v[22:23], v[130:131] op_sel:[0,1]
	s_nop 0
	v_pk_fma_f32 v[66:67], v[18:19], v[130:131], v[64:65] neg_lo:[0,0,1] neg_hi:[0,0,1]
	v_pk_fma_f32 v[64:65], v[18:19], v[130:131], v[64:65] op_sel_hi:[1,0,1]
	s_nop 0
	v_mov_b32_e32 v67, v65
	s_waitcnt vmcnt(32)
	v_pk_add_f32 v[132:133], v[132:133], v[66:67]
	s_nop 0
	v_pk_mul_f32 v[64:65], v[22:23], v[132:133] op_sel:[0,1]
	s_nop 0
	v_pk_fma_f32 v[66:67], v[18:19], v[132:133], v[64:65] neg_lo:[0,0,1] neg_hi:[0,0,1]
	v_pk_fma_f32 v[64:65], v[18:19], v[132:133], v[64:65] op_sel_hi:[1,0,1]
	s_nop 0
	v_mov_b32_e32 v67, v65
	s_waitcnt vmcnt(31)
	v_pk_add_f32 v[134:135], v[134:135], v[66:67]
	s_nop 0
	v_pk_mul_f32 v[64:65], v[22:23], v[134:135] op_sel:[0,1]
	s_nop 0
	v_pk_fma_f32 v[66:67], v[18:19], v[134:135], v[64:65] neg_lo:[0,0,1] neg_hi:[0,0,1]
	v_pk_fma_f32 v[64:65], v[18:19], v[134:135], v[64:65] op_sel_hi:[1,0,1]
	s_nop 0
	v_mov_b32_e32 v67, v65
	s_waitcnt vmcnt(30)
	v_pk_add_f32 v[136:137], v[136:137], v[66:67]
	s_nop 0
	v_pk_mul_f32 v[64:65], v[22:23], v[136:137] op_sel:[0,1]
	s_nop 0
	v_pk_fma_f32 v[66:67], v[18:19], v[136:137], v[64:65] neg_lo:[0,0,1] neg_hi:[0,0,1]
	v_pk_fma_f32 v[64:65], v[18:19], v[136:137], v[64:65] op_sel_hi:[1,0,1]
	s_nop 0
	v_mov_b32_e32 v67, v65
	s_waitcnt vmcnt(29)
	v_pk_add_f32 v[138:139], v[138:139], v[66:67]
	s_nop 0
	v_pk_mul_f32 v[64:65], v[22:23], v[138:139] op_sel:[0,1]
	s_nop 0
	v_pk_fma_f32 v[66:67], v[18:19], v[138:139], v[64:65] neg_lo:[0,0,1] neg_hi:[0,0,1]
	v_pk_fma_f32 v[64:65], v[18:19], v[138:139], v[64:65] op_sel_hi:[1,0,1]
	s_nop 0
	v_mov_b32_e32 v67, v65
	s_waitcnt vmcnt(28)
	v_pk_add_f32 v[140:141], v[140:141], v[66:67]
	s_nop 0
	v_pk_mul_f32 v[64:65], v[22:23], v[140:141] op_sel:[0,1]
	s_nop 0
	v_pk_fma_f32 v[66:67], v[18:19], v[140:141], v[64:65] neg_lo:[0,0,1] neg_hi:[0,0,1]
	v_pk_fma_f32 v[64:65], v[18:19], v[140:141], v[64:65] op_sel_hi:[1,0,1]
	s_nop 0
	v_mov_b32_e32 v67, v65
	s_waitcnt vmcnt(27)
	v_pk_add_f32 v[142:143], v[142:143], v[66:67]
	s_nop 0
	v_pk_mul_f32 v[64:65], v[22:23], v[142:143] op_sel:[0,1]
	s_nop 0
	v_pk_fma_f32 v[66:67], v[18:19], v[142:143], v[64:65] neg_lo:[0,0,1] neg_hi:[0,0,1]
	v_pk_fma_f32 v[64:65], v[18:19], v[142:143], v[64:65] op_sel_hi:[1,0,1]
	s_nop 0
	v_mov_b32_e32 v67, v65
	s_waitcnt vmcnt(26)
	v_pk_add_f32 v[144:145], v[144:145], v[66:67]
	s_nop 0
	v_pk_mul_f32 v[64:65], v[24:25], v[144:145] op_sel:[0,1] op_sel_hi:[1,0]
	s_nop 0
	v_pk_fma_f32 v[66:67], v[20:21], v[144:145], v[64:65] neg_lo:[0,0,1] neg_hi:[0,0,1]
	v_pk_fma_f32 v[64:65], v[20:21], v[144:145], v[64:65]
	s_nop 0
	v_mov_b32_e32 v67, v65
	s_waitcnt vmcnt(25)
	v_pk_add_f32 v[146:147], v[146:147], v[66:67]
	s_nop 0
	v_pk_mul_f32 v[64:65], v[22:23], v[146:147] op_sel:[0,1]
	s_nop 0
	v_pk_fma_f32 v[66:67], v[18:19], v[146:147], v[64:65] neg_lo:[0,0,1] neg_hi:[0,0,1]
	v_pk_fma_f32 v[64:65], v[18:19], v[146:147], v[64:65] op_sel_hi:[1,0,1]
	s_nop 0
	v_mov_b32_e32 v67, v65
	s_waitcnt vmcnt(24)
	v_pk_add_f32 v[148:149], v[148:149], v[66:67]
	s_nop 0
	v_pk_mul_f32 v[64:65], v[22:23], v[148:149] op_sel:[0,1]
	s_nop 0
	v_pk_fma_f32 v[66:67], v[18:19], v[148:149], v[64:65] neg_lo:[0,0,1] neg_hi:[0,0,1]
	v_pk_fma_f32 v[64:65], v[18:19], v[148:149], v[64:65] op_sel_hi:[1,0,1]
	s_nop 0
	v_mov_b32_e32 v67, v65
	s_waitcnt vmcnt(23)
	v_pk_add_f32 v[150:151], v[150:151], v[66:67]
	s_nop 0
	v_pk_mul_f32 v[64:65], v[22:23], v[150:151] op_sel:[0,1]
	s_nop 0
	v_pk_fma_f32 v[66:67], v[18:19], v[150:151], v[64:65] neg_lo:[0,0,1] neg_hi:[0,0,1]
	v_pk_fma_f32 v[64:65], v[18:19], v[150:151], v[64:65] op_sel_hi:[1,0,1]
	s_nop 0
	v_mov_b32_e32 v67, v65
	s_waitcnt vmcnt(22)
	v_pk_add_f32 v[152:153], v[152:153], v[66:67]
	s_nop 0
	v_pk_mul_f32 v[64:65], v[22:23], v[152:153] op_sel:[0,1]
	s_nop 0
	v_pk_fma_f32 v[66:67], v[18:19], v[152:153], v[64:65] neg_lo:[0,0,1] neg_hi:[0,0,1]
	v_pk_fma_f32 v[64:65], v[18:19], v[152:153], v[64:65] op_sel_hi:[1,0,1]
	s_nop 0
	v_mov_b32_e32 v67, v65
	s_waitcnt vmcnt(21)
	v_pk_add_f32 v[154:155], v[154:155], v[66:67]
	s_nop 0
	v_pk_mul_f32 v[64:65], v[22:23], v[154:155] op_sel:[0,1]
	s_nop 0
	v_pk_fma_f32 v[66:67], v[18:19], v[154:155], v[64:65] neg_lo:[0,0,1] neg_hi:[0,0,1]
	v_pk_fma_f32 v[64:65], v[18:19], v[154:155], v[64:65] op_sel_hi:[1,0,1]
	s_nop 0
	v_mov_b32_e32 v67, v65
	s_waitcnt vmcnt(20)
	v_pk_add_f32 v[156:157], v[156:157], v[66:67]
	s_nop 0
	v_pk_mul_f32 v[64:65], v[22:23], v[156:157] op_sel:[0,1]
	s_nop 0
	v_pk_fma_f32 v[66:67], v[18:19], v[156:157], v[64:65] neg_lo:[0,0,1] neg_hi:[0,0,1]
	v_pk_fma_f32 v[64:65], v[18:19], v[156:157], v[64:65] op_sel_hi:[1,0,1]
	s_nop 0
	v_mov_b32_e32 v67, v65
	s_waitcnt vmcnt(19)
	v_pk_add_f32 v[158:159], v[158:159], v[66:67]
	s_nop 0
	v_pk_mul_f32 v[64:65], v[22:23], v[158:159] op_sel:[0,1]
	s_nop 0
	v_pk_fma_f32 v[66:67], v[18:19], v[158:159], v[64:65] neg_lo:[0,0,1] neg_hi:[0,0,1]
	v_pk_fma_f32 v[64:65], v[18:19], v[158:159], v[64:65] op_sel_hi:[1,0,1]
	s_nop 0
	v_mov_b32_e32 v67, v65
	s_waitcnt vmcnt(18)
	v_pk_add_f32 v[160:161], v[160:161], v[66:67]
	s_nop 0
	v_pk_mul_f32 v[64:65], v[24:25], v[160:161] op_sel:[0,1] op_sel_hi:[1,0]
	s_nop 0
	v_pk_fma_f32 v[66:67], v[20:21], v[160:161], v[64:65] neg_lo:[0,0,1] neg_hi:[0,0,1]
	v_pk_fma_f32 v[64:65], v[20:21], v[160:161], v[64:65]
	s_nop 0
	v_mov_b32_e32 v67, v65
	s_waitcnt vmcnt(17)
	v_pk_add_f32 v[162:163], v[162:163], v[66:67]
	s_nop 0
	v_pk_mul_f32 v[64:65], v[22:23], v[162:163] op_sel:[0,1]
	s_nop 0
	v_pk_fma_f32 v[66:67], v[18:19], v[162:163], v[64:65] neg_lo:[0,0,1] neg_hi:[0,0,1]
	v_pk_fma_f32 v[64:65], v[18:19], v[162:163], v[64:65] op_sel_hi:[1,0,1]
	s_nop 0
	v_mov_b32_e32 v67, v65
	s_waitcnt vmcnt(16)
	v_pk_add_f32 v[164:165], v[164:165], v[66:67]
	s_nop 0
	v_pk_mul_f32 v[64:65], v[22:23], v[164:165] op_sel:[0,1]
	s_nop 0
	v_pk_fma_f32 v[66:67], v[18:19], v[164:165], v[64:65] neg_lo:[0,0,1] neg_hi:[0,0,1]
	v_pk_fma_f32 v[64:65], v[18:19], v[164:165], v[64:65] op_sel_hi:[1,0,1]
	s_nop 0
	v_mov_b32_e32 v67, v65
	s_waitcnt vmcnt(15)
	v_pk_add_f32 v[166:167], v[166:167], v[66:67]
	s_nop 0
	v_pk_mul_f32 v[64:65], v[22:23], v[166:167] op_sel:[0,1]
	s_nop 0
	v_pk_fma_f32 v[66:67], v[18:19], v[166:167], v[64:65] neg_lo:[0,0,1] neg_hi:[0,0,1]
	v_pk_fma_f32 v[64:65], v[18:19], v[166:167], v[64:65] op_sel_hi:[1,0,1]
	s_nop 0
	v_mov_b32_e32 v67, v65
	s_waitcnt vmcnt(14)
	v_pk_add_f32 v[168:169], v[168:169], v[66:67]
	s_nop 0
	v_pk_mul_f32 v[64:65], v[22:23], v[168:169] op_sel:[0,1]
	s_nop 0
	v_pk_fma_f32 v[66:67], v[18:19], v[168:169], v[64:65] neg_lo:[0,0,1] neg_hi:[0,0,1]
	v_pk_fma_f32 v[64:65], v[18:19], v[168:169], v[64:65] op_sel_hi:[1,0,1]
	s_nop 0
	v_mov_b32_e32 v67, v65
	s_waitcnt vmcnt(13)
	v_pk_add_f32 v[170:171], v[170:171], v[66:67]
	s_nop 0
	v_pk_mul_f32 v[64:65], v[22:23], v[170:171] op_sel:[0,1]
	s_nop 0
	v_pk_fma_f32 v[66:67], v[18:19], v[170:171], v[64:65] neg_lo:[0,0,1] neg_hi:[0,0,1]
	v_pk_fma_f32 v[64:65], v[18:19], v[170:171], v[64:65] op_sel_hi:[1,0,1]
	s_nop 0
	v_mov_b32_e32 v67, v65
	s_waitcnt vmcnt(12)
	v_pk_add_f32 v[172:173], v[172:173], v[66:67]
	s_nop 0
	v_pk_mul_f32 v[64:65], v[22:23], v[172:173] op_sel:[0,1]
	s_nop 0
	v_pk_fma_f32 v[66:67], v[18:19], v[172:173], v[64:65] neg_lo:[0,0,1] neg_hi:[0,0,1]
	v_pk_fma_f32 v[64:65], v[18:19], v[172:173], v[64:65] op_sel_hi:[1,0,1]
	s_nop 0
	v_mov_b32_e32 v67, v65
	s_waitcnt vmcnt(11)
	v_pk_add_f32 v[174:175], v[174:175], v[66:67]
	s_nop 0
	v_pk_mul_f32 v[64:65], v[22:23], v[174:175] op_sel:[0,1]
	s_nop 0
	v_pk_fma_f32 v[66:67], v[18:19], v[174:175], v[64:65] neg_lo:[0,0,1] neg_hi:[0,0,1]
	v_pk_fma_f32 v[64:65], v[18:19], v[174:175], v[64:65] op_sel_hi:[1,0,1]
	s_nop 0
	v_mov_b32_e32 v67, v65
	s_waitcnt vmcnt(10)
	v_pk_add_f32 v[176:177], v[176:177], v[66:67]
	s_nop 0
	v_pk_mul_f32 v[64:65], v[24:25], v[176:177] op_sel:[0,1] op_sel_hi:[1,0]
	s_nop 0
	v_pk_fma_f32 v[66:67], v[20:21], v[176:177], v[64:65] neg_lo:[0,0,1] neg_hi:[0,0,1]
	v_pk_fma_f32 v[64:65], v[20:21], v[176:177], v[64:65]
	s_nop 0
	v_mov_b32_e32 v67, v65
	s_waitcnt vmcnt(9)
	v_pk_add_f32 v[178:179], v[178:179], v[66:67]
	s_nop 0
	v_pk_mul_f32 v[64:65], v[22:23], v[178:179] op_sel:[0,1]
	s_nop 0
	v_pk_fma_f32 v[66:67], v[18:19], v[178:179], v[64:65] neg_lo:[0,0,1] neg_hi:[0,0,1]
	v_pk_fma_f32 v[64:65], v[18:19], v[178:179], v[64:65] op_sel_hi:[1,0,1]
	s_nop 0
	v_mov_b32_e32 v67, v65
	s_waitcnt vmcnt(8)
	v_pk_add_f32 v[180:181], v[180:181], v[66:67]
	s_nop 0
	v_pk_mul_f32 v[64:65], v[22:23], v[180:181] op_sel:[0,1]
	s_nop 0
	v_pk_fma_f32 v[66:67], v[18:19], v[180:181], v[64:65] neg_lo:[0,0,1] neg_hi:[0,0,1]
	v_pk_fma_f32 v[64:65], v[18:19], v[180:181], v[64:65] op_sel_hi:[1,0,1]
	s_nop 0
	v_mov_b32_e32 v67, v65
	s_waitcnt vmcnt(7)
	v_pk_add_f32 v[182:183], v[182:183], v[66:67]
	s_nop 0
	v_pk_mul_f32 v[64:65], v[22:23], v[182:183] op_sel:[0,1]
	s_nop 0
	v_pk_fma_f32 v[66:67], v[18:19], v[182:183], v[64:65] neg_lo:[0,0,1] neg_hi:[0,0,1]
	v_pk_fma_f32 v[64:65], v[18:19], v[182:183], v[64:65] op_sel_hi:[1,0,1]
	s_nop 0
	v_mov_b32_e32 v67, v65
	s_waitcnt vmcnt(6)
	v_pk_add_f32 v[184:185], v[184:185], v[66:67]
	s_nop 0
	v_pk_mul_f32 v[64:65], v[22:23], v[184:185] op_sel:[0,1]
	s_nop 0
	v_pk_fma_f32 v[66:67], v[18:19], v[184:185], v[64:65] neg_lo:[0,0,1] neg_hi:[0,0,1]
	v_pk_fma_f32 v[64:65], v[18:19], v[184:185], v[64:65] op_sel_hi:[1,0,1]
	s_nop 0
	v_mov_b32_e32 v67, v65
	s_waitcnt vmcnt(5)
	v_pk_add_f32 v[186:187], v[186:187], v[66:67]
	s_nop 0
	v_pk_mul_f32 v[64:65], v[22:23], v[186:187] op_sel:[0,1]
	s_nop 0
	v_pk_fma_f32 v[66:67], v[18:19], v[186:187], v[64:65] neg_lo:[0,0,1] neg_hi:[0,0,1]
	v_pk_fma_f32 v[64:65], v[18:19], v[186:187], v[64:65] op_sel_hi:[1,0,1]
	s_nop 0
	v_mov_b32_e32 v67, v65
	s_waitcnt vmcnt(4)
	v_pk_add_f32 v[188:189], v[188:189], v[66:67]
	s_nop 0
	v_pk_mul_f32 v[64:65], v[22:23], v[188:189] op_sel:[0,1]
	s_nop 0
	v_pk_fma_f32 v[66:67], v[18:19], v[188:189], v[64:65] neg_lo:[0,0,1] neg_hi:[0,0,1]
	v_pk_fma_f32 v[64:65], v[18:19], v[188:189], v[64:65] op_sel_hi:[1,0,1]
	s_nop 0
	v_mov_b32_e32 v67, v65
	s_waitcnt vmcnt(3)
	v_pk_add_f32 v[190:191], v[190:191], v[66:67]
	s_nop 0
	v_pk_mul_f32 v[64:65], v[22:23], v[190:191] op_sel:[0,1]
	s_nop 0
	v_pk_fma_f32 v[66:67], v[18:19], v[190:191], v[64:65] neg_lo:[0,0,1] neg_hi:[0,0,1]
	v_pk_fma_f32 v[64:65], v[18:19], v[190:191], v[64:65] op_sel_hi:[1,0,1]
	s_nop 0
	v_mov_b32_e32 v67, v65
	s_waitcnt vmcnt(2)
	v_pk_add_f32 v[192:193], v[192:193], v[66:67]
	s_nop 0
	v_pk_mul_f32 v[64:65], v[24:25], v[192:193] op_sel:[0,1] op_sel_hi:[1,0]
	s_nop 0
	v_pk_fma_f32 v[66:67], v[20:21], v[192:193], v[64:65] neg_lo:[0,0,1] neg_hi:[0,0,1]
	v_pk_fma_f32 v[64:65], v[20:21], v[192:193], v[64:65]
	s_nop 0
	v_mov_b32_e32 v67, v65
	s_waitcnt vmcnt(1)
	v_pk_add_f32 v[194:195], v[194:195], v[66:67]
	s_nop 0
	global_store_dwordx2 v[200:201], v[68:69], off
	v_lshl_add_u64 v[200:201], v[200:201], 0, v[198:199]
	global_store_dwordx2 v[200:201], v[70:71], off
	v_lshl_add_u64 v[200:201], v[200:201], 0, v[198:199]
	global_store_dwordx2 v[200:201], v[72:73], off
	v_lshl_add_u64 v[200:201], v[200:201], 0, v[198:199]
	global_store_dwordx2 v[200:201], v[74:75], off
	v_lshl_add_u64 v[200:201], v[200:201], 0, v[198:199]
	global_store_dwordx2 v[200:201], v[76:77], off
	v_lshl_add_u64 v[200:201], v[200:201], 0, v[198:199]
	global_store_dwordx2 v[200:201], v[78:79], off
	v_lshl_add_u64 v[200:201], v[200:201], 0, v[198:199]
	global_store_dwordx2 v[200:201], v[80:81], off
	v_lshl_add_u64 v[200:201], v[200:201], 0, v[198:199]
	global_store_dwordx2 v[200:201], v[82:83], off
	v_lshl_add_u64 v[200:201], v[200:201], 0, v[198:199]
	global_store_dwordx2 v[200:201], v[84:85], off
	v_lshl_add_u64 v[200:201], v[200:201], 0, v[198:199]
	global_store_dwordx2 v[200:201], v[86:87], off
	v_lshl_add_u64 v[200:201], v[200:201], 0, v[198:199]
	global_store_dwordx2 v[200:201], v[88:89], off
	v_lshl_add_u64 v[200:201], v[200:201], 0, v[198:199]
	global_store_dwordx2 v[200:201], v[90:91], off
	v_lshl_add_u64 v[200:201], v[200:201], 0, v[198:199]
	global_store_dwordx2 v[200:201], v[92:93], off
	v_lshl_add_u64 v[200:201], v[200:201], 0, v[198:199]
	global_store_dwordx2 v[200:201], v[94:95], off
	v_lshl_add_u64 v[200:201], v[200:201], 0, v[198:199]
	global_store_dwordx2 v[200:201], v[96:97], off
	v_lshl_add_u64 v[200:201], v[200:201], 0, v[198:199]
	global_store_dwordx2 v[200:201], v[98:99], off
	v_lshl_add_u64 v[200:201], v[200:201], 0, v[198:199]
	global_store_dwordx2 v[200:201], v[100:101], off
	v_lshl_add_u64 v[200:201], v[200:201], 0, v[198:199]
	global_store_dwordx2 v[200:201], v[102:103], off
	v_lshl_add_u64 v[200:201], v[200:201], 0, v[198:199]
	global_store_dwordx2 v[200:201], v[104:105], off
	v_lshl_add_u64 v[200:201], v[200:201], 0, v[198:199]
	global_store_dwordx2 v[200:201], v[106:107], off
	v_lshl_add_u64 v[200:201], v[200:201], 0, v[198:199]
	global_store_dwordx2 v[200:201], v[108:109], off
	v_lshl_add_u64 v[200:201], v[200:201], 0, v[198:199]
	global_store_dwordx2 v[200:201], v[110:111], off
	v_lshl_add_u64 v[200:201], v[200:201], 0, v[198:199]
	global_store_dwordx2 v[200:201], v[112:113], off
	v_lshl_add_u64 v[200:201], v[200:201], 0, v[198:199]
	global_store_dwordx2 v[200:201], v[114:115], off
	v_lshl_add_u64 v[200:201], v[200:201], 0, v[198:199]
	global_store_dwordx2 v[200:201], v[116:117], off
	v_lshl_add_u64 v[200:201], v[200:201], 0, v[198:199]
	global_store_dwordx2 v[200:201], v[118:119], off
	v_lshl_add_u64 v[200:201], v[200:201], 0, v[198:199]
	global_store_dwordx2 v[200:201], v[120:121], off
	v_lshl_add_u64 v[200:201], v[200:201], 0, v[198:199]
	global_store_dwordx2 v[200:201], v[122:123], off
	v_lshl_add_u64 v[200:201], v[200:201], 0, v[198:199]
	global_store_dwordx2 v[200:201], v[124:125], off
	v_lshl_add_u64 v[200:201], v[200:201], 0, v[198:199]
	global_store_dwordx2 v[200:201], v[126:127], off
	v_lshl_add_u64 v[200:201], v[200:201], 0, v[198:199]
	global_store_dwordx2 v[200:201], v[128:129], off
	v_lshl_add_u64 v[200:201], v[200:201], 0, v[198:199]
	global_store_dwordx2 v[200:201], v[130:131], off
	v_lshl_add_u64 v[200:201], v[200:201], 0, v[198:199]
	global_store_dwordx2 v[200:201], v[132:133], off
	v_lshl_add_u64 v[200:201], v[200:201], 0, v[198:199]
	global_store_dwordx2 v[200:201], v[134:135], off
	v_lshl_add_u64 v[200:201], v[200:201], 0, v[198:199]
	global_store_dwordx2 v[200:201], v[136:137], off
	v_lshl_add_u64 v[200:201], v[200:201], 0, v[198:199]
	global_store_dwordx2 v[200:201], v[138:139], off
	v_lshl_add_u64 v[200:201], v[200:201], 0, v[198:199]
	global_store_dwordx2 v[200:201], v[140:141], off
	v_lshl_add_u64 v[200:201], v[200:201], 0, v[198:199]
	global_store_dwordx2 v[200:201], v[142:143], off
	v_lshl_add_u64 v[200:201], v[200:201], 0, v[198:199]
	global_store_dwordx2 v[200:201], v[144:145], off
	v_lshl_add_u64 v[200:201], v[200:201], 0, v[198:199]
	global_store_dwordx2 v[200:201], v[146:147], off
	v_lshl_add_u64 v[200:201], v[200:201], 0, v[198:199]
	global_store_dwordx2 v[200:201], v[148:149], off
	v_lshl_add_u64 v[200:201], v[200:201], 0, v[198:199]
	global_store_dwordx2 v[200:201], v[150:151], off
	v_lshl_add_u64 v[200:201], v[200:201], 0, v[198:199]
	global_store_dwordx2 v[200:201], v[152:153], off
	v_lshl_add_u64 v[200:201], v[200:201], 0, v[198:199]
	global_store_dwordx2 v[200:201], v[154:155], off
	v_lshl_add_u64 v[200:201], v[200:201], 0, v[198:199]
	global_store_dwordx2 v[200:201], v[156:157], off
	v_lshl_add_u64 v[200:201], v[200:201], 0, v[198:199]
	global_store_dwordx2 v[200:201], v[158:159], off
	v_lshl_add_u64 v[200:201], v[200:201], 0, v[198:199]
	global_store_dwordx2 v[200:201], v[160:161], off
	v_lshl_add_u64 v[200:201], v[200:201], 0, v[198:199]
	global_store_dwordx2 v[200:201], v[162:163], off
	v_lshl_add_u64 v[200:201], v[200:201], 0, v[198:199]
	global_store_dwordx2 v[200:201], v[164:165], off
	v_lshl_add_u64 v[200:201], v[200:201], 0, v[198:199]
	global_store_dwordx2 v[200:201], v[166:167], off
	v_lshl_add_u64 v[200:201], v[200:201], 0, v[198:199]
	global_store_dwordx2 v[200:201], v[168:169], off
	v_lshl_add_u64 v[200:201], v[200:201], 0, v[198:199]
	global_store_dwordx2 v[200:201], v[170:171], off
	v_lshl_add_u64 v[200:201], v[200:201], 0, v[198:199]
	global_store_dwordx2 v[200:201], v[172:173], off
	v_lshl_add_u64 v[200:201], v[200:201], 0, v[198:199]
	global_store_dwordx2 v[200:201], v[174:175], off
	v_lshl_add_u64 v[200:201], v[200:201], 0, v[198:199]
	global_store_dwordx2 v[200:201], v[176:177], off
	v_lshl_add_u64 v[200:201], v[200:201], 0, v[198:199]
	global_store_dwordx2 v[200:201], v[178:179], off
	v_lshl_add_u64 v[200:201], v[200:201], 0, v[198:199]
	global_store_dwordx2 v[200:201], v[180:181], off
	v_lshl_add_u64 v[200:201], v[200:201], 0, v[198:199]
	global_store_dwordx2 v[200:201], v[182:183], off
	v_lshl_add_u64 v[200:201], v[200:201], 0, v[198:199]
	global_store_dwordx2 v[200:201], v[184:185], off
	v_lshl_add_u64 v[200:201], v[200:201], 0, v[198:199]
	global_store_dwordx2 v[200:201], v[186:187], off
	v_lshl_add_u64 v[200:201], v[200:201], 0, v[198:199]
	global_store_dwordx2 v[200:201], v[188:189], off
	v_lshl_add_u64 v[200:201], v[200:201], 0, v[198:199]
	global_store_dwordx2 v[200:201], v[190:191], off
	v_lshl_add_u64 v[200:201], v[200:201], 0, v[198:199]
	global_store_dwordx2 v[200:201], v[192:193], off
	v_mov_b32_e32 v16, v194
	v_mov_b32_e32 v17, v195
	s_branch .Ls5scan_done

.Ls5scan_done:
	s_or_b64 exec, exec, s[8:9]
	s_and_saveexec_b64 s[0:1], vcc
	s_cbranch_execz .LBB0_1076
	v_ashrrev_i32_e32 v15, 31, v14
	v_lshlrev_b64 v[14:15], 2, v[14:15]
	v_or_b32_e32 v14, v14, v54
	v_or_b32_e32 v14, s11, v14
	v_lshlrev_b64 v[14:15], 12, v[14:15]
	v_lshl_add_u64 v[14:15], v[8:9], 0, v[14:15]
	v_lshlrev_b32_e32 v228, 8, v53
	v_lshl_add_u64 v[14:15], v[14:15], 0, v[228:229]
	v_lshlrev_b32_e32 v228, 2, v4
	v_lshl_add_u64 v[14:15], v[14:15], 0, v[228:229]
	v_add_co_u32_e32 v18, vcc, 0x2000000, v14
	s_nop 1
	v_addc_co_u32_e32 v19, vcc, 0, v15, vcc
	v_add_co_u32_e32 v14, vcc, 0x2040000, v14
	flat_store_dword v[18:19], v16
	s_nop 0
	v_addc_co_u32_e32 v15, vcc, 0, v15, vcc
	flat_store_dword v[14:15], v17
	s_branch .LBB0_1076

.LBB0_2181:
	s_or_b64 exec, exec, s[0:1]
	v_readlane_b32 s0, v255, 9
	s_mul_i32 s50, s0, 0x10800
	s_mul_i32 s6, s0, 0x5800
	s_mov_b32 s7, s51
	s_mov_b32 s10, 0
	s_waitcnt lgkmcnt(0)
	s_barrier
	s_getreg_b32 s0, hwreg(HW_REG_LDS_ALLOC, 0, 8)
	s_cmp_eq_u32 s0, 0
	s_cbranch_scc1 .Lgu_nostagger
	s_sleep 100
.Lgu_nostagger:
	s_branch .LBB0_2184
